# peephole: adjacent 32-bit register copy pairs merged into v_mov_b64 (130 sites, incl. the m2 scan steps)
# speedup vs baseline: 1.0063x; 1.0018x over previous
.LBB0_323:
	s_and_b32 s6, s12, 0xffffffe0
	v_or_b32_e32 v6, s6, v21
	v_ashrrev_i32_e32 v7, 31, v6
	v_lshlrev_b64 v[6:7], 11, v[6:7]
	s_and_b32 s15, s14, 15
	v_add_u32_e32 v250, s6, v8
	v_ashrrev_i32_e32 v251, 31, v250
	v_lshlrev_b64 v[250:251], 11, v[250:251]
	v_lshl_add_u64 v[250:251], s[8:9], 0, v[250:251]
	s_lshl_b32 s24, s15, 7
	v_lshl_add_u64 v[250:251], v[250:251], 0, s[24:25]
	v_mov_b32_e32 v252, v4
	v_mov_b32_e32 v253, v20
	v_lshl_add_u64 v[250:251], v[250:251], 0, v[252:253]
	global_load_dwordx2 v[252:253], v[250:251], off
	v_lshl_add_u64 v[6:7], v[0:1], 0, v[6:7]
	v_lshlrev_b32_e32 v5, 11, v21
	v_lshl_or_b32 v16, s15, 17, v5
	v_mov_b32_e32 v17, v20
	v_add_co_u32_e32 v78, vcc, 0x8000, v6
	v_lshl_add_u64 v[86:87], v[2:3], 0, v[16:17]
	s_nop 0
	v_addc_co_u32_e32 v79, vcc, 0, v7, vcc
	v_add_co_u32_e32 v94, vcc, 0x8000, v86
	s_mov_b32 s7, 0x18000
	s_nop 0
	v_addc_co_u32_e32 v95, vcc, 0, v87, vcc
	v_add_co_u32_e32 v102, vcc, s80, v86
	s_nop 1
	v_addc_co_u32_e32 v103, vcc, 0, v87, vcc
	v_add_co_u32_e32 v110, vcc, s7, v86
	s_nop 1
	v_addc_co_u32_e32 v111, vcc, 0, v87, vcc
	global_load_dwordx4 v[16:19], v[6:7], off
	global_load_dwordx4 v[22:25], v[6:7], off offset:64
	global_load_dwordx4 v[26:29], v[78:79], off
	global_load_dwordx4 v[30:33], v[78:79], off offset:64
	global_load_dwordx4 v[34:37], v[86:87], off
	global_load_dwordx4 v[38:41], v[86:87], off offset:64
	global_load_dwordx4 v[42:45], v[94:95], off
	global_load_dwordx4 v[46:49], v[94:95], off offset:64
	global_load_dwordx4 v[50:53], v[102:103], off
	global_load_dwordx4 v[54:57], v[102:103], off offset:64
	global_load_dwordx4 v[58:61], v[110:111], off
	global_load_dwordx4 v[62:65], v[110:111], off offset:64
	global_load_dwordx4 v[66:69], v[6:7], off offset:128
	global_load_dwordx4 v[70:73], v[6:7], off offset:192
	global_load_dwordx4 v[74:77], v[78:79], off offset:128
	s_nop 0
	global_load_dwordx4 v[78:81], v[78:79], off offset:192
	s_nop 0
	global_load_dwordx4 v[82:85], v[86:87], off offset:128
	s_nop 0
	global_load_dwordx4 v[86:89], v[86:87], off offset:192
	s_nop 0
	global_load_dwordx4 v[90:93], v[94:95], off offset:128
	s_nop 0
	global_load_dwordx4 v[94:97], v[94:95], off offset:192
	s_nop 0
	global_load_dwordx4 v[98:101], v[102:103], off offset:128
	s_nop 0
	global_load_dwordx4 v[102:105], v[102:103], off offset:192
	s_nop 0
	global_load_dwordx4 v[106:109], v[110:111], off offset:128
	s_nop 0
	global_load_dwordx4 v[110:113], v[110:111], off offset:192
	s_waitcnt vmcnt(19)
	v_mfma_f32_16x16x32_bf16 v[114:117], v[34:37], v[16:19], 0
	s_waitcnt vmcnt(17)
	v_mfma_f32_16x16x32_bf16 v[118:121], v[42:45], v[16:19], 0
	s_waitcnt vmcnt(15)
	v_mfma_f32_16x16x32_bf16 v[122:125], v[50:53], v[16:19], 0
	s_waitcnt vmcnt(13)
	v_mfma_f32_16x16x32_bf16 v[16:19], v[58:61], v[16:19], 0
	v_mfma_f32_16x16x32_bf16 v[34:37], v[34:37], v[26:29], 0
	v_mfma_f32_16x16x32_bf16 v[42:45], v[42:45], v[26:29], 0
	v_mfma_f32_16x16x32_bf16 v[50:53], v[50:53], v[26:29], 0
	v_mfma_f32_16x16x32_bf16 v[26:29], v[58:61], v[26:29], 0
	v_mfma_f32_16x16x32_bf16 v[58:61], v[38:41], v[22:25], v[114:117]
	v_mfma_f32_16x16x32_bf16 v[114:117], v[46:49], v[22:25], v[118:121]
	v_mfma_f32_16x16x32_bf16 v[118:121], v[54:57], v[22:25], v[122:125]
	s_waitcnt vmcnt(12)
	v_mfma_f32_16x16x32_bf16 v[16:19], v[62:65], v[22:25], v[16:19]
	v_mfma_f32_16x16x32_bf16 v[22:25], v[38:41], v[30:33], v[34:37]
	v_mfma_f32_16x16x32_bf16 v[34:37], v[46:49], v[30:33], v[42:45]
	v_mfma_f32_16x16x32_bf16 v[38:41], v[54:57], v[30:33], v[50:53]
	v_mfma_f32_16x16x32_bf16 v[26:29], v[62:65], v[30:33], v[26:29]
	s_waitcnt vmcnt(7)
	v_mfma_f32_16x16x32_bf16 v[30:33], v[82:85], v[66:69], v[58:61]
	s_waitcnt vmcnt(5)
	v_mfma_f32_16x16x32_bf16 v[42:45], v[90:93], v[66:69], v[114:117]
	s_waitcnt vmcnt(3)
	v_mfma_f32_16x16x32_bf16 v[46:49], v[98:101], v[66:69], v[118:121]
	s_waitcnt vmcnt(1)
	v_mfma_f32_16x16x32_bf16 v[16:19], v[106:109], v[66:69], v[16:19]
	v_mfma_f32_16x16x32_bf16 v[22:25], v[82:85], v[74:77], v[22:25]
	v_mfma_f32_16x16x32_bf16 v[34:37], v[90:93], v[74:77], v[34:37]
	v_mfma_f32_16x16x32_bf16 v[38:41], v[98:101], v[74:77], v[38:41]
	v_mfma_f32_16x16x32_bf16 v[26:29], v[106:109], v[74:77], v[26:29]
	v_mfma_f32_16x16x32_bf16 v[30:33], v[86:89], v[70:73], v[30:33]
	v_mfma_f32_16x16x32_bf16 v[42:45], v[94:97], v[70:73], v[42:45]
	v_mfma_f32_16x16x32_bf16 v[46:49], v[102:105], v[70:73], v[46:49]
	s_waitcnt vmcnt(0)
	v_mfma_f32_16x16x32_bf16 v[16:19], v[110:113], v[70:73], v[16:19]
	v_mfma_f32_16x16x32_bf16 v[22:25], v[86:89], v[78:81], v[22:25]
	v_mfma_f32_16x16x32_bf16 v[34:37], v[94:97], v[78:81], v[34:37]
	v_mfma_f32_16x16x32_bf16 v[38:41], v[102:105], v[78:81], v[38:41]
	v_mfma_f32_16x16x32_bf16 v[26:29], v[110:113], v[78:81], v[26:29]
	ds_write_b128 v14, v[30:33]
	ds_write_b128 v14, v[42:45] offset:64
	ds_write_b128 v14, v[46:49] offset:128
	s_nop 0
	ds_write_b128 v14, v[16:19] offset:192
	ds_write_b128 v14, v[22:25] offset:4096
	ds_write_b128 v14, v[34:37] offset:4160
	ds_write_b128 v14, v[38:41] offset:4224
	ds_write_b128 v14, v[26:29] offset:4288
	s_waitcnt lgkmcnt(0)
	s_barrier
	ds_read_b128 v[16:19], v9
	ds_read_b128 v[22:25], v9 offset:8192
	s_lshl_b32 s24, s15, 7
	v_mov_b32_e32 v5, v20
	s_waitcnt lgkmcnt(0)
	v_pk_add_f32 v[6:7], v[18:19], v[24:25]
	v_pk_add_f32 v[22:23], v[16:17], v[22:23]
	ds_read_b128 v[16:19], v9 offset:16384
	s_waitcnt lgkmcnt(0)
	v_pk_add_f32 v[6:7], v[6:7], v[18:19]
	v_pk_add_f32 v[22:23], v[22:23], v[16:17]
	ds_read_b128 v[16:19], v9 offset:24576
	s_waitcnt lgkmcnt(0)
	v_pk_add_f32 v[6:7], v[6:7], v[18:19]
	v_pk_add_f32 v[22:23], v[22:23], v[16:17]
	ds_read_b128 v[16:19], v9 offset:32768
	s_waitcnt lgkmcnt(0)
	v_pk_add_f32 v[6:7], v[6:7], v[18:19]
	v_pk_add_f32 v[22:23], v[22:23], v[16:17]
	ds_read_b128 v[16:19], v9 offset:40960
	s_waitcnt lgkmcnt(0)
	v_pk_add_f32 v[6:7], v[6:7], v[18:19]
	v_pk_add_f32 v[22:23], v[22:23], v[16:17]
	ds_read_b128 v[16:19], v9 offset:49152
	s_waitcnt lgkmcnt(0)
	v_pk_add_f32 v[6:7], v[6:7], v[18:19]
	v_pk_add_f32 v[22:23], v[22:23], v[16:17]
	ds_read_b128 v[16:19], v9 offset:57344
	s_waitcnt lgkmcnt(0)
	v_pk_add_f32 v[18:19], v[6:7], v[18:19]
	v_add_u32_e32 v6, s6, v8
	v_ashrrev_i32_e32 v7, 31, v6
	v_pk_add_f32 v[16:17], v[22:23], v[16:17]
	v_lshlrev_b64 v[22:23], 11, v[6:7]
	v_lshl_add_u64 v[22:23], s[8:9], 0, v[22:23]
	v_lshl_add_u64 v[22:23], v[22:23], 0, s[24:25]
	v_lshl_add_u64 v[22:23], v[22:23], 0, v[4:5]
	v_mov_b64_e32 v[24:25], v[252:253]
	s_waitcnt vmcnt(0)
	v_lshlrev_b32_e32 v26, 16, v24
	v_and_b32_e32 v27, 0xffff0000, v24
	v_lshlrev_b32_e32 v24, 16, v25
	v_and_b32_e32 v25, 0xffff0000, v25
	v_pk_add_f32 v[18:19], v[18:19], v[24:25]
	v_pk_add_f32 v[16:17], v[16:17], v[26:27]
	v_mul_f32_e32 v15, v19, v19
	v_mul_f32_e32 v5, v17, v17
	v_fmac_f32_e32 v5, v16, v16
	v_fmac_f32_e32 v15, v18, v18
	v_add_f32_e32 v5, v5, v15
	ds_bpermute_b32 v15, v10, v5
	v_cvt_pk_bf16_f32 v24, v16, v17
	v_cvt_pk_bf16_f32 v25, v18, v19
	global_store_dwordx2 v[22:23], v[24:25], off
	s_waitcnt lgkmcnt(0)
	v_add_f32_e32 v5, v5, v15
	ds_bpermute_b32 v15, v11, v5
	s_waitcnt lgkmcnt(0)
	v_add_f32_e32 v5, v5, v15
	ds_bpermute_b32 v15, v12, v5
	s_waitcnt lgkmcnt(0)
	v_add_f32_e32 v5, v5, v15
	ds_bpermute_b32 v15, v13, v5
	s_and_saveexec_b64 s[6:7], s[38:39]
	s_cbranch_execz .LBB0_322
	v_lshlrev_b64 v[6:7], 6, v[6:7]
	v_lshl_add_u64 v[6:7], s[10:11], 0, v[6:7]
	s_lshl_b32 s24, s15, 2
	s_waitcnt lgkmcnt(0)
	v_add_f32_e32 v5, v5, v15
	v_lshl_add_u64 v[6:7], v[6:7], 0, s[24:25]
	global_store_dword v[6:7], v5, off
	s_branch .LBB0_322

.LBB0_392:
	v_lshl_or_b32 v38, v40, 4, v76
	s_waitcnt vmcnt(4)
	v_mfma_f32_16x16x32_bf16 v[164:167], v[66:69], v[30:33], 0
	v_ashrrev_i32_e32 v39, 31, v38
	v_add_u32_e32 v154, v79, v130
	v_lshlrev_b64 v[38:39], 8, v[38:39]
	v_mfma_f32_16x16x32_bf16 v[168:171], v[66:69], v[34:37], 0
	v_ashrrev_i32_e32 v155, 31, v154
	v_lshl_add_u64 v[38:39], v[88:89], 0, v[38:39]
	v_lshl_add_u64 v[154:155], v[154:155], 2, s[52:53]
	v_add_u32_e32 v149, 0x400, v136
	s_waitcnt vmcnt(3)
	v_lshlrev_b32_e32 v184, 16, v41
	s_waitcnt vmcnt(2)
	v_lshlrev_b32_e32 v183, 16, v42
	s_waitcnt vmcnt(1)
	v_lshlrev_b32_e32 v182, 16, v43
	s_waitcnt vmcnt(0)
	v_lshlrev_b32_e32 v181, 16, v44
	global_load_dwordx4 v[50:53], v[38:39], off
	global_load_dwordx4 v[46:49], v[38:39], off offset:64
	global_load_dwordx4 v[42:45], v[38:39], off offset:128
	s_nop 0
	global_load_dwordx4 v[38:41], v[38:39], off offset:192
	v_cndmask_b32_e64 v129, v3, v1, s[8:9]
	global_load_dword v145, v[154:155], off
	ds_write2_b32 v136, v164, v168 offset1:16
	ds_write2_b32 v136, v165, v169 offset0:132 offset1:148
	ds_write2_b32 v149, v166, v170 offset0:8 offset1:24
	ds_write2_b32 v149, v167, v171 offset0:140 offset1:156
	v_mfma_f32_16x16x32_bf16 v[164:167], v[66:69], v[22:25], 0
	v_cndmask_b32_e64 v155, v73, v71, s[8:9]
	v_cndmask_b32_e64 v154, v72, v70, s[8:9]
	v_mov_b32_e32 v132, v129
	v_mfma_f32_16x16x32_bf16 v[168:171], v[66:69], v[26:29], 0
	s_nop 7
	ds_write2_b32 v136, v164, v168 offset0:32 offset1:48
	ds_write2_b32 v136, v165, v169 offset0:164 offset1:180
	ds_write2_b32 v149, v166, v170 offset0:40 offset1:56
	ds_write2_b32 v149, v167, v171 offset0:172 offset1:188
	v_mfma_f32_16x16x32_bf16 v[164:167], v[66:69], v[16:19], 0
	v_cndmask_b32_e64 v128, v2, v0, s[8:9]
	v_add_u32_e32 v163, 32, v137
	v_add_u32_e32 v176, 0xf0, v137
	v_mfma_f32_16x16x32_bf16 v[168:171], v[66:69], v[12:15], 0
	s_nop 7
	ds_write2_b32 v136, v164, v168 offset0:64 offset1:80
	ds_write2_b32 v136, v165, v169 offset0:196 offset1:212
	ds_write2_b32 v149, v166, v170 offset0:72 offset1:88
	ds_write2_b32 v149, v167, v171 offset0:204 offset1:220
	v_mfma_f32_16x16x32_bf16 v[164:167], v[66:69], v[8:11], 0
	v_lshl_add_u32 v130, v130, 1, v139
	s_and_b64 vcc, exec, s[38:39]
	v_mfma_f32_16x16x32_bf16 v[66:69], v[66:69], v[4:7], 0
	s_nop 7
	ds_write2_b32 v136, v164, v66 offset0:96 offset1:112
	ds_write2_b32 v136, v165, v67 offset0:228 offset1:244
	ds_write2_b32 v149, v166, v68 offset0:104 offset1:120
	ds_write2_b32 v149, v167, v69 offset0:236 offset1:252
	s_waitcnt lgkmcnt(0)
	ds_read2st64_b32 v[212:213], v137 offset1:1
	v_add_u32_e32 v207, 16, v137
	ds_read2st64_b32 v[214:215], v207 offset0:2 offset1:3
	v_add_u32_e32 v207, 32, v137
	ds_read2st64_b32 v[216:217], v207 offset0:4 offset1:5
	v_add_u32_e32 v207, 48, v137
	ds_read2st64_b32 v[218:219], v207 offset0:6 offset1:7
	v_add_u32_e32 v207, 64, v137
	ds_read2st64_b32 v[220:221], v207 offset0:8 offset1:9
	v_add_u32_e32 v207, 80, v137
	ds_read2st64_b32 v[222:223], v207 offset0:10 offset1:11
	v_add_u32_e32 v207, 96, v137
	ds_read2st64_b32 v[224:225], v207 offset0:12 offset1:13
	v_add_u32_e32 v207, 112, v137
	ds_read2st64_b32 v[226:227], v207 offset0:14 offset1:15
	v_add_u32_e32 v207, 128, v137
	ds_read2st64_b32 v[228:229], v207 offset0:16 offset1:17
	v_add_u32_e32 v207, 144, v137
	ds_read2st64_b32 v[230:231], v207 offset0:18 offset1:19
	v_add_u32_e32 v207, 160, v137
	ds_read2st64_b32 v[232:233], v207 offset0:20 offset1:21
	v_add_u32_e32 v207, 176, v137
	ds_read2st64_b32 v[234:235], v207 offset0:22 offset1:23
	v_add_u32_e32 v207, 192, v137
	ds_read2st64_b32 v[236:237], v207 offset0:24 offset1:25
	v_add_u32_e32 v207, 208, v137
	ds_read2st64_b32 v[238:239], v207 offset0:26 offset1:27
	v_add_u32_e32 v207, 224, v137
	ds_read2st64_b32 v[240:241], v207 offset0:28 offset1:29
	v_add_u32_e32 v207, 240, v137
	ds_read2st64_b32 v[242:243], v207 offset0:30 offset1:31
	s_waitcnt lgkmcnt(15)
	v_fma_f32 v212, v128, v154, v212
	v_fma_f32 v213, v128, v155, v213
	v_fma_f32 v212, -v132, v155, v212
	v_fma_f32 v213, v132, v154, v213
	v_mov_b64_e32 v[154:155], v[212:213]
	v_mov_b32_e32 v66, v128
	v_cvt_pk_bf16_f32 v156, v154, v155
	ds_write_b16 v138, v156
	ds_write_b16_d16_hi v138, v156 offset:128
	s_waitcnt lgkmcnt(15)
	v_fma_f32 v214, v128, v154, v214
	v_fma_f32 v215, v128, v155, v215
	v_fma_f32 v214, -v132, v155, v214
	v_fma_f32 v215, v132, v154, v215
	v_mov_b64_e32 v[154:155], v[214:215]
	v_mov_b32_e32 v67, v128
	v_cvt_pk_bf16_f32 v156, v154, v155
	ds_write_b16 v138, v156 offset:272
	ds_write_b16_d16_hi v138, v156 offset:400
	s_waitcnt lgkmcnt(15)
	v_fma_f32 v216, v128, v154, v216
	v_fma_f32 v217, v128, v155, v217
	v_fma_f32 v216, -v132, v155, v216
	v_fma_f32 v217, v132, v154, v217
	v_mov_b64_e32 v[154:155], v[216:217]
	v_add_u32_e32 v164, 48, v137
	v_cvt_pk_bf16_f32 v156, v154, v155
	ds_write_b16 v138, v156 offset:544
	ds_write_b16_d16_hi v138, v156 offset:672
	s_waitcnt lgkmcnt(15)
	v_fma_f32 v218, v128, v154, v218
	v_fma_f32 v219, v128, v155, v219
	v_fma_f32 v218, -v132, v155, v218
	v_fma_f32 v219, v132, v154, v219
	v_mov_b64_e32 v[154:155], v[218:219]
	v_add_u32_e32 v165, 64, v137
	v_cvt_pk_bf16_f32 v156, v154, v155
	ds_write_b16 v138, v156 offset:816
	ds_write_b16_d16_hi v138, v156 offset:944
	s_waitcnt lgkmcnt(15)
	v_fma_f32 v220, v128, v154, v220
	v_fma_f32 v221, v128, v155, v221
	v_fma_f32 v220, -v132, v155, v220
	v_fma_f32 v221, v132, v154, v221
	v_mov_b64_e32 v[154:155], v[220:221]
	v_add_u32_e32 v166, 0x50, v137
	v_cvt_pk_bf16_f32 v156, v154, v155
	ds_write_b16 v138, v156 offset:1088
	ds_write_b16_d16_hi v138, v156 offset:1216
	s_waitcnt lgkmcnt(15)
	v_fma_f32 v222, v128, v154, v222
	v_fma_f32 v223, v128, v155, v223
	v_fma_f32 v222, -v132, v155, v222
	v_fma_f32 v223, v132, v154, v223
	v_mov_b64_e32 v[154:155], v[222:223]
	v_add_u32_e32 v167, 0x60, v137
	v_cvt_pk_bf16_f32 v156, v154, v155
	ds_write_b16 v138, v156 offset:1360
	ds_write_b16_d16_hi v138, v156 offset:1488
	s_waitcnt lgkmcnt(15)
	v_fma_f32 v224, v128, v154, v224
	v_fma_f32 v225, v128, v155, v225
	v_fma_f32 v224, -v132, v155, v224
	v_fma_f32 v225, v132, v154, v225
	v_mov_b64_e32 v[154:155], v[224:225]
	v_add_u32_e32 v168, 0x70, v137
	v_cvt_pk_bf16_f32 v156, v154, v155
	ds_write_b16 v138, v156 offset:1632
	ds_write_b16_d16_hi v138, v156 offset:1760
	s_waitcnt lgkmcnt(15)
	v_fma_f32 v226, v128, v154, v226
	v_fma_f32 v227, v128, v155, v227
	v_fma_f32 v226, -v132, v155, v226
	v_fma_f32 v227, v132, v154, v227
	v_mov_b64_e32 v[154:155], v[226:227]
	v_add_u32_e32 v169, 0x80, v137
	v_cvt_pk_bf16_f32 v156, v154, v155
	ds_write_b16 v138, v156 offset:1904
	ds_write_b16_d16_hi v138, v156 offset:2032
	s_waitcnt lgkmcnt(15)
	v_fma_f32 v228, v128, v154, v228
	v_fma_f32 v229, v128, v155, v229
	v_fma_f32 v228, -v132, v155, v228
	v_fma_f32 v229, v132, v154, v229
	v_mov_b64_e32 v[154:155], v[228:229]
	v_add_u32_e32 v170, 0x90, v137
	v_cvt_pk_bf16_f32 v156, v154, v155
	ds_write_b16 v138, v156 offset:2176
	ds_write_b16_d16_hi v138, v156 offset:2304
	s_waitcnt lgkmcnt(15)
	v_fma_f32 v230, v128, v154, v230
	v_fma_f32 v231, v128, v155, v231
	v_fma_f32 v230, -v132, v155, v230
	v_fma_f32 v231, v132, v154, v231
	v_mov_b64_e32 v[154:155], v[230:231]
	v_add_u32_e32 v171, 0xa0, v137
	v_cvt_pk_bf16_f32 v156, v154, v155
	ds_write_b16 v138, v156 offset:2448
	ds_write_b16_d16_hi v138, v156 offset:2576
	s_waitcnt lgkmcnt(15)
	v_fma_f32 v232, v128, v154, v232
	v_fma_f32 v233, v128, v155, v233
	v_fma_f32 v232, -v132, v155, v232
	v_fma_f32 v233, v132, v154, v233
	v_mov_b64_e32 v[154:155], v[232:233]
	v_add_u32_e32 v172, 0xb0, v137
	v_cvt_pk_bf16_f32 v156, v154, v155
	ds_write_b16 v138, v156 offset:2720
	ds_write_b16_d16_hi v138, v156 offset:2848
	s_waitcnt lgkmcnt(15)
	v_fma_f32 v234, v128, v154, v234
	v_fma_f32 v235, v128, v155, v235
	v_fma_f32 v234, -v132, v155, v234
	v_fma_f32 v235, v132, v154, v235
	v_mov_b64_e32 v[154:155], v[234:235]
	v_add_u32_e32 v173, 0xc0, v137
	v_cvt_pk_bf16_f32 v156, v154, v155
	ds_write_b16 v138, v156 offset:2992
	ds_write_b16_d16_hi v138, v156 offset:3120
	s_waitcnt lgkmcnt(15)
	v_fma_f32 v236, v128, v154, v236
	v_fma_f32 v237, v128, v155, v237
	v_fma_f32 v236, -v132, v155, v236
	v_fma_f32 v237, v132, v154, v237
	v_mov_b64_e32 v[154:155], v[236:237]
	v_add_u32_e32 v174, 0xd0, v137
	v_cvt_pk_bf16_f32 v156, v154, v155
	ds_write_b16 v138, v156 offset:3264
	ds_write_b16_d16_hi v138, v156 offset:3392
	s_waitcnt lgkmcnt(15)
	v_fma_f32 v238, v128, v154, v238
	v_fma_f32 v239, v128, v155, v239
	v_fma_f32 v238, -v132, v155, v238
	v_fma_f32 v239, v132, v154, v239
	v_mov_b64_e32 v[154:155], v[238:239]
	v_add_u32_e32 v175, 0xe0, v137
	v_cvt_pk_bf16_f32 v156, v154, v155
	ds_write_b16 v138, v156 offset:3536
	ds_write_b16_d16_hi v138, v156 offset:3664
	s_waitcnt lgkmcnt(15)
	v_fma_f32 v240, v128, v154, v240
	v_fma_f32 v241, v128, v155, v241
	v_fma_f32 v240, -v132, v155, v240
	v_fma_f32 v241, v132, v154, v241
	v_mov_b64_e32 v[154:155], v[240:241]
	v_mov_b32_e32 v68, v129
	v_cvt_pk_bf16_f32 v156, v154, v155
	ds_write_b16 v138, v156 offset:3808
	ds_write_b16_d16_hi v138, v156 offset:3936
	v_mov_b32_e32 v69, v129
	s_waitcnt lgkmcnt(15)
	v_fma_f32 v242, v128, v154, v242
	v_fma_f32 v243, v128, v155, v243
	v_fma_f32 v242, -v132, v155, v242
	v_fma_f32 v243, v132, v154, v243
	v_mov_b64_e32 v[128:129], v[242:243]
	s_nop 0
	v_cvt_pk_bf16_f32 v132, v128, v129
	ds_write_b16 v138, v132 offset:4080
	ds_write_b16_d16_hi v138, v132 offset:4208
	s_waitcnt lgkmcnt(0)
	ds_read_b128 v[186:189], v140
	ds_read_b128 v[208:211], v140 offset:64
	s_waitcnt vmcnt(4) lgkmcnt(1)
	v_mfma_f32_16x16x32_bf16 v[186:189], v[186:189], v[50:53], 0
	s_waitcnt vmcnt(3) lgkmcnt(0)
	v_mfma_f32_16x16x32_bf16 v[186:189], v[208:211], v[46:49], v[186:189]
	ds_read_b128 v[208:211], v140 offset:128
	s_waitcnt vmcnt(2) lgkmcnt(0)
	v_mfma_f32_16x16x32_bf16 v[186:189], v[208:211], v[42:45], v[186:189]
	ds_read_b128 v[208:211], v140 offset:192
	s_waitcnt vmcnt(1) lgkmcnt(0)
	v_mfma_f32_16x16x32_bf16 v[186:189], v[208:211], v[38:41], v[186:189]
	s_waitcnt vmcnt(0)
	s_nop 6
	v_fma_f32 v132, v145, v184, v186
	v_mul_f32_e32 v154, 0x3d372713, v132
	v_mul_f32_e32 v154, v132, v154
	v_fma_f32 v154, v132, v154, v132
	v_mul_f32_e32 v154, 0xbfcc422a, v154
	v_mul_f32_e32 v154, 0x3fb8aa3b, v154
	v_exp_f32_e32 v154, v154
	v_fmac_f32_e32 v189, v145, v181
	v_add_f32_e32 v154, 1.0, v154
	v_rcp_f32_e32 v154, v154
	s_nop 0
	v_mul_f32_e32 v132, v132, v154
	v_cvt_pk_bf16_f32 v132, v132, v20
	ds_write_b16 v130, v132
	v_fma_f32 v132, v145, v183, v187
	v_mul_f32_e32 v154, 0x3d372713, v132
	v_mul_f32_e32 v154, v132, v154
	v_fma_f32 v154, v132, v154, v132
	v_mul_f32_e32 v154, 0xbfcc422a, v154
	v_mul_f32_e32 v154, 0x3fb8aa3b, v154
	v_exp_f32_e32 v154, v154
	s_nop 0
	v_add_f32_e32 v154, 1.0, v154
	v_rcp_f32_e32 v154, v154
	s_nop 0
	v_mul_f32_e32 v132, v132, v154
	v_cvt_pk_bf16_f32 v132, v132, v20
	ds_write_b16 v130, v132 offset:528
	v_fma_f32 v132, v145, v182, v188
	v_mul_f32_e32 v154, 0x3d372713, v132
	v_mul_f32_e32 v154, v132, v154
	v_fma_f32 v154, v132, v154, v132
	v_mul_f32_e32 v154, 0xbfcc422a, v154
	v_mul_f32_e32 v154, 0x3fb8aa3b, v154
	v_exp_f32_e32 v154, v154
	s_nop 0
	v_add_f32_e32 v154, 1.0, v154
	v_rcp_f32_e32 v154, v154
	s_nop 0
	v_mul_f32_e32 v132, v132, v154
	v_cvt_pk_bf16_f32 v132, v132, v20
	ds_write_b16 v130, v132 offset:1056
	v_mul_f32_e32 v132, 0x3d372713, v189
	v_mul_f32_e32 v132, v189, v132
	v_fma_f32 v132, v189, v132, v189
	v_mul_f32_e32 v132, 0xbfcc422a, v132
	v_mul_f32_e32 v132, 0x3fb8aa3b, v132
	v_exp_f32_e32 v132, v132
	s_nop 0
	v_add_f32_e32 v132, 1.0, v132
	v_rcp_f32_e32 v132, v132
	s_nop 0
	v_mul_f32_e32 v132, v189, v132
	v_cvt_pk_bf16_f32 v132, v132, v20
	ds_write_b16 v130, v132 offset:1584
	s_waitcnt lgkmcnt(0)
	s_cbranch_vccnz .LBB0_396
	v_mfma_f32_16x16x32_bf16 v[182:185], v[62:65], v[30:33], 0
	v_mfma_f32_16x16x32_bf16 v[186:189], v[62:65], v[34:37], 0
	s_nop 7
	ds_write2_b32 v136, v182, v186 offset1:16
	ds_write2_b32 v136, v183, v187 offset0:132 offset1:148
	ds_write2_b32 v149, v184, v188 offset0:8 offset1:24
	ds_write2_b32 v149, v185, v189 offset0:140 offset1:156
	v_mfma_f32_16x16x32_bf16 v[182:185], v[62:65], v[22:25], 0
	v_mfma_f32_16x16x32_bf16 v[186:189], v[62:65], v[26:29], 0
	s_nop 7
	ds_write2_b32 v136, v182, v186 offset0:32 offset1:48
	ds_write2_b32 v136, v183, v187 offset0:164 offset1:180
	ds_write2_b32 v149, v184, v188 offset0:40 offset1:56
	ds_write2_b32 v149, v185, v189 offset0:172 offset1:188
	v_mfma_f32_16x16x32_bf16 v[182:185], v[62:65], v[16:19], 0
	v_mfma_f32_16x16x32_bf16 v[186:189], v[62:65], v[12:15], 0
	s_nop 7
	ds_write2_b32 v136, v182, v186 offset0:64 offset1:80
	ds_write2_b32 v136, v183, v187 offset0:196 offset1:212
	ds_write2_b32 v149, v184, v188 offset0:72 offset1:88
	ds_write2_b32 v149, v185, v189 offset0:204 offset1:220
	v_mfma_f32_16x16x32_bf16 v[182:185], v[62:65], v[8:11], 0
	v_mfma_f32_16x16x32_bf16 v[62:65], v[62:65], v[4:7], 0
	s_nop 7
	ds_write2_b32 v136, v182, v62 offset0:96 offset1:112
	ds_write2_b32 v136, v183, v63 offset0:228 offset1:244
	ds_write2_b32 v149, v184, v64 offset0:104 offset1:120
	ds_write2_b32 v149, v185, v65 offset0:236 offset1:252
	s_waitcnt lgkmcnt(0)
	ds_read2st64_b32 v[212:213], v137 offset1:1
	v_add_u32_e32 v207, 16, v137
	ds_read2st64_b32 v[214:215], v207 offset0:2 offset1:3
	v_add_u32_e32 v207, 32, v137
	ds_read2st64_b32 v[216:217], v207 offset0:4 offset1:5
	v_add_u32_e32 v207, 48, v137
	ds_read2st64_b32 v[218:219], v207 offset0:6 offset1:7
	v_add_u32_e32 v207, 64, v137
	ds_read2st64_b32 v[220:221], v207 offset0:8 offset1:9
	v_add_u32_e32 v207, 80, v137
	ds_read2st64_b32 v[222:223], v207 offset0:10 offset1:11
	v_add_u32_e32 v207, 96, v137
	ds_read2st64_b32 v[224:225], v207 offset0:12 offset1:13
	v_add_u32_e32 v207, 112, v137
	ds_read2st64_b32 v[226:227], v207 offset0:14 offset1:15
	v_add_u32_e32 v207, 128, v137
	ds_read2st64_b32 v[228:229], v207 offset0:16 offset1:17
	v_add_u32_e32 v207, 144, v137
	ds_read2st64_b32 v[230:231], v207 offset0:18 offset1:19
	v_add_u32_e32 v207, 160, v137
	ds_read2st64_b32 v[232:233], v207 offset0:20 offset1:21
	v_add_u32_e32 v207, 176, v137
	ds_read2st64_b32 v[234:235], v207 offset0:22 offset1:23
	v_add_u32_e32 v207, 192, v137
	ds_read2st64_b32 v[236:237], v207 offset0:24 offset1:25
	v_add_u32_e32 v207, 208, v137
	ds_read2st64_b32 v[238:239], v207 offset0:26 offset1:27
	v_add_u32_e32 v207, 224, v137
	ds_read2st64_b32 v[240:241], v207 offset0:28 offset1:29
	v_add_u32_e32 v207, 240, v137
	ds_read2st64_b32 v[242:243], v207 offset0:30 offset1:31
	s_nop 0
	s_nop 0
	s_waitcnt lgkmcnt(15)
	v_fma_f32 v212, v66, v128, v212
	v_fma_f32 v213, v66, v129, v213
	v_fma_f32 v212, -v68, v129, v212
	v_fma_f32 v213, v68, v128, v213
	v_mov_b64_e32 v[62:63], v[212:213]
	s_nop 0
	v_cvt_pk_bf16_f32 v64, v62, v63
	ds_write_b16 v138, v64
	ds_write_b16_d16_hi v138, v64 offset:128
	s_nop 0
	s_nop 0
	s_waitcnt lgkmcnt(15)
	v_fma_f32 v214, v66, v62, v214
	v_fma_f32 v215, v66, v63, v215
	v_fma_f32 v214, -v68, v63, v214
	v_fma_f32 v215, v68, v62, v215
	v_mov_b64_e32 v[62:63], v[214:215]
	s_nop 0
	v_cvt_pk_bf16_f32 v64, v62, v63
	ds_write_b16 v138, v64 offset:272
	ds_write_b16_d16_hi v138, v64 offset:400
	s_nop 0
	s_nop 0
	s_waitcnt lgkmcnt(15)
	v_fma_f32 v216, v66, v62, v216
	v_fma_f32 v217, v66, v63, v217
	v_fma_f32 v216, -v68, v63, v216
	v_fma_f32 v217, v68, v62, v217
	v_mov_b64_e32 v[62:63], v[216:217]
	s_nop 0
	v_cvt_pk_bf16_f32 v64, v62, v63
	ds_write_b16 v138, v64 offset:544
	ds_write_b16_d16_hi v138, v64 offset:672
	s_nop 0
	s_nop 0
	s_waitcnt lgkmcnt(15)
	v_fma_f32 v218, v66, v62, v218
	v_fma_f32 v219, v66, v63, v219
	v_fma_f32 v218, -v68, v63, v218
	v_fma_f32 v219, v68, v62, v219
	v_mov_b64_e32 v[62:63], v[218:219]
	s_nop 0
	v_cvt_pk_bf16_f32 v64, v62, v63
	ds_write_b16 v138, v64 offset:816
	ds_write_b16_d16_hi v138, v64 offset:944
	s_nop 0
	s_nop 0
	s_waitcnt lgkmcnt(15)
	v_fma_f32 v220, v66, v62, v220
	v_fma_f32 v221, v66, v63, v221
	v_fma_f32 v220, -v68, v63, v220
	v_fma_f32 v221, v68, v62, v221
	v_mov_b64_e32 v[62:63], v[220:221]
	s_nop 0
	v_cvt_pk_bf16_f32 v64, v62, v63
	ds_write_b16 v138, v64 offset:1088
	ds_write_b16_d16_hi v138, v64 offset:1216
	s_nop 0
	s_nop 0
	s_waitcnt lgkmcnt(15)
	v_fma_f32 v222, v66, v62, v222
	v_fma_f32 v223, v66, v63, v223
	v_fma_f32 v222, -v68, v63, v222
	v_fma_f32 v223, v68, v62, v223
	v_mov_b64_e32 v[62:63], v[222:223]
	s_nop 0
	v_cvt_pk_bf16_f32 v64, v62, v63
	ds_write_b16 v138, v64 offset:1360
	ds_write_b16_d16_hi v138, v64 offset:1488
	s_nop 0
	s_nop 0
	s_waitcnt lgkmcnt(15)
	v_fma_f32 v224, v66, v62, v224
	v_fma_f32 v225, v66, v63, v225
	v_fma_f32 v224, -v68, v63, v224
	v_fma_f32 v225, v68, v62, v225
	v_mov_b64_e32 v[62:63], v[224:225]
	s_nop 0
	v_cvt_pk_bf16_f32 v64, v62, v63
	ds_write_b16 v138, v64 offset:1632
	ds_write_b16_d16_hi v138, v64 offset:1760
	s_nop 0
	s_nop 0
	s_waitcnt lgkmcnt(15)
	v_fma_f32 v226, v66, v62, v226
	v_fma_f32 v227, v66, v63, v227
	v_fma_f32 v226, -v68, v63, v226
	v_fma_f32 v227, v68, v62, v227
	v_mov_b64_e32 v[62:63], v[226:227]
	s_nop 0
	v_cvt_pk_bf16_f32 v64, v62, v63
	ds_write_b16 v138, v64 offset:1904
	ds_write_b16_d16_hi v138, v64 offset:2032
	s_nop 0
	s_nop 0
	s_waitcnt lgkmcnt(15)
	v_fma_f32 v228, v66, v62, v228
	v_fma_f32 v229, v66, v63, v229
	v_fma_f32 v228, -v68, v63, v228
	v_fma_f32 v229, v68, v62, v229
	v_mov_b64_e32 v[62:63], v[228:229]
	s_nop 0
	v_cvt_pk_bf16_f32 v64, v62, v63
	ds_write_b16 v138, v64 offset:2176
	ds_write_b16_d16_hi v138, v64 offset:2304
	s_nop 0
	s_nop 0
	s_waitcnt lgkmcnt(15)
	v_fma_f32 v230, v66, v62, v230
	v_fma_f32 v231, v66, v63, v231
	v_fma_f32 v230, -v68, v63, v230
	v_fma_f32 v231, v68, v62, v231
	v_mov_b64_e32 v[62:63], v[230:231]
	s_nop 0
	v_cvt_pk_bf16_f32 v64, v62, v63
	ds_write_b16 v138, v64 offset:2448
	ds_write_b16_d16_hi v138, v64 offset:2576
	s_nop 0
	s_nop 0
	s_waitcnt lgkmcnt(15)
	v_fma_f32 v232, v66, v62, v232
	v_fma_f32 v233, v66, v63, v233
	v_fma_f32 v232, -v68, v63, v232
	v_fma_f32 v233, v68, v62, v233
	v_mov_b64_e32 v[62:63], v[232:233]
	s_nop 0
	v_cvt_pk_bf16_f32 v64, v62, v63
	ds_write_b16 v138, v64 offset:2720
	ds_write_b16_d16_hi v138, v64 offset:2848
	s_nop 0
	s_nop 0
	s_waitcnt lgkmcnt(15)
	v_fma_f32 v234, v66, v62, v234
	v_fma_f32 v235, v66, v63, v235
	v_fma_f32 v234, -v68, v63, v234
	v_fma_f32 v235, v68, v62, v235
	v_mov_b64_e32 v[62:63], v[234:235]
	s_nop 0
	v_cvt_pk_bf16_f32 v64, v62, v63
	ds_write_b16 v138, v64 offset:2992
	ds_write_b16_d16_hi v138, v64 offset:3120
	s_nop 0
	s_nop 0
	s_waitcnt lgkmcnt(15)
	v_fma_f32 v236, v66, v62, v236
	v_fma_f32 v237, v66, v63, v237
	v_fma_f32 v236, -v68, v63, v236
	v_fma_f32 v237, v68, v62, v237
	v_mov_b64_e32 v[62:63], v[236:237]
	s_nop 0
	v_cvt_pk_bf16_f32 v64, v62, v63
	ds_write_b16 v138, v64 offset:3264
	ds_write_b16_d16_hi v138, v64 offset:3392
	s_nop 0
	s_nop 0
	s_waitcnt lgkmcnt(15)
	v_fma_f32 v238, v66, v62, v238
	v_fma_f32 v239, v66, v63, v239
	v_fma_f32 v238, -v68, v63, v238
	v_fma_f32 v239, v68, v62, v239
	v_mov_b64_e32 v[62:63], v[238:239]
	s_nop 0
	v_cvt_pk_bf16_f32 v64, v62, v63
	ds_write_b16 v138, v64 offset:3536
	ds_write_b16_d16_hi v138, v64 offset:3664
	s_nop 0
	s_nop 0
	s_waitcnt lgkmcnt(15)
	v_fma_f32 v240, v66, v62, v240
	v_fma_f32 v241, v66, v63, v241
	v_fma_f32 v240, -v68, v63, v240
	v_fma_f32 v241, v68, v62, v241
	v_mov_b64_e32 v[62:63], v[240:241]
	s_nop 0
	v_cvt_pk_bf16_f32 v64, v62, v63
	ds_write_b16 v138, v64 offset:3808
	ds_write_b16_d16_hi v138, v64 offset:3936
	s_nop 0
	s_nop 0
	s_waitcnt lgkmcnt(15)
	v_fma_f32 v242, v66, v62, v242
	v_fma_f32 v243, v66, v63, v243
	v_fma_f32 v242, -v68, v63, v242
	v_fma_f32 v243, v68, v62, v243
	v_mov_b64_e32 v[128:129], v[242:243]
	s_nop 0
	v_cvt_pk_bf16_f32 v62, v128, v129
	ds_write_b16 v138, v62 offset:4080
	ds_write_b16_d16_hi v138, v62 offset:4208
	s_waitcnt lgkmcnt(0)
	ds_read_b128 v[62:65], v140
	ds_read_b128 v[182:185], v140 offset:64
	s_waitcnt lgkmcnt(1)
	v_mfma_f32_16x16x32_bf16 v[62:65], v[62:65], v[50:53], 0
	s_waitcnt lgkmcnt(0)
	v_mfma_f32_16x16x32_bf16 v[62:65], v[182:185], v[46:49], v[62:65]
	ds_read_b128 v[182:185], v140 offset:128
	s_waitcnt lgkmcnt(0)
	v_mfma_f32_16x16x32_bf16 v[62:65], v[182:185], v[42:45], v[62:65]
	ds_read_b128 v[182:185], v140 offset:192
	s_waitcnt lgkmcnt(0)
	v_mfma_f32_16x16x32_bf16 v[62:65], v[182:185], v[38:41], v[62:65]
	s_nop 7
	v_fma_f32 v62, v180, v145, v62
	v_mul_f32_e32 v132, 0x3d372713, v62
	v_mul_f32_e32 v132, v62, v132
	v_fma_f32 v132, v62, v132, v62
	v_mul_f32_e32 v132, 0xbfcc422a, v132
	v_mul_f32_e32 v132, 0x3fb8aa3b, v132
	v_exp_f32_e32 v132, v132
	v_fmac_f32_e32 v65, v177, v145
	v_add_f32_e32 v132, 1.0, v132
	v_rcp_f32_e32 v132, v132
	s_nop 0
	v_mul_f32_e32 v62, v62, v132
	v_cvt_pk_bf16_f32 v62, v62, v20
	ds_write_b16 v130, v62 offset:8448
	v_fma_f32 v62, v179, v145, v63
	v_mul_f32_e32 v63, 0x3d372713, v62
	v_mul_f32_e32 v63, v62, v63
	v_fma_f32 v63, v62, v63, v62
	v_mul_f32_e32 v63, 0xbfcc422a, v63
	v_mul_f32_e32 v63, 0x3fb8aa3b, v63
	v_exp_f32_e32 v63, v63
	s_nop 0
	v_add_f32_e32 v63, 1.0, v63
	v_rcp_f32_e32 v63, v63
	s_nop 0
	v_mul_f32_e32 v62, v62, v63
	v_cvt_pk_bf16_f32 v62, v62, v20
	ds_write_b16 v130, v62 offset:8976
	v_fma_f32 v62, v178, v145, v64
	v_mul_f32_e32 v63, 0x3d372713, v62
	v_mul_f32_e32 v63, v62, v63
	v_fma_f32 v63, v62, v63, v62
	v_mul_f32_e32 v63, 0xbfcc422a, v63
	v_mul_f32_e32 v63, 0x3fb8aa3b, v63
	v_exp_f32_e32 v63, v63
	s_nop 0
	v_add_f32_e32 v63, 1.0, v63
	v_rcp_f32_e32 v63, v63
	s_nop 0
	v_mul_f32_e32 v62, v62, v63
	v_cvt_pk_bf16_f32 v62, v62, v20
	ds_write_b16 v130, v62 offset:9504
	v_mul_f32_e32 v62, 0x3d372713, v65
	v_mul_f32_e32 v62, v65, v62
	v_fma_f32 v62, v65, v62, v65
	v_mul_f32_e32 v62, 0xbfcc422a, v62
	v_mul_f32_e32 v62, 0x3fb8aa3b, v62
	v_exp_f32_e32 v62, v62
	s_nop 0
	v_add_f32_e32 v62, 1.0, v62
	v_rcp_f32_e32 v62, v62
	s_nop 0
	v_mul_f32_e32 v62, v65, v62
	v_cvt_pk_bf16_f32 v62, v62, v20
	ds_write_b16 v130, v62 offset:10032
	s_waitcnt lgkmcnt(0)
	s_and_b64 vcc, exec, s[38:39]
	s_cbranch_vccz .LBB0_397

.LBB0_395:
	v_mfma_f32_16x16x32_bf16 v[30:33], v[54:57], v[30:33], 0
	v_mfma_f32_16x16x32_bf16 v[34:37], v[54:57], v[34:37], 0
	s_nop 7
	ds_write2_b32 v136, v30, v34 offset1:16
	ds_write2_b32 v136, v31, v35 offset0:132 offset1:148
	ds_write2_b32 v149, v32, v36 offset0:8 offset1:24
	v_mfma_f32_16x16x32_bf16 v[22:25], v[54:57], v[22:25], 0
	v_mfma_f32_16x16x32_bf16 v[26:29], v[54:57], v[26:29], 0
	ds_write2_b32 v149, v33, v37 offset0:140 offset1:156
	s_nop 6
	ds_write2_b32 v136, v22, v26 offset0:32 offset1:48
	ds_write2_b32 v136, v23, v27 offset0:164 offset1:180
	v_mfma_f32_16x16x32_bf16 v[16:19], v[54:57], v[16:19], 0
	v_mfma_f32_16x16x32_bf16 v[12:15], v[54:57], v[12:15], 0
	ds_write2_b32 v149, v24, v28 offset0:40 offset1:56
	ds_write2_b32 v149, v25, v29 offset0:172 offset1:188
	s_nop 5
	ds_write2_b32 v136, v16, v12 offset0:64 offset1:80
	ds_write2_b32 v136, v17, v13 offset0:196 offset1:212
	ds_write2_b32 v149, v18, v14 offset0:72 offset1:88
	ds_write2_b32 v149, v19, v15 offset0:204 offset1:220
	v_mfma_f32_16x16x32_bf16 v[8:11], v[54:57], v[8:11], 0
	v_mfma_f32_16x16x32_bf16 v[4:7], v[54:57], v[4:7], 0
	s_nop 7
	ds_write2_b32 v136, v8, v4 offset0:96 offset1:112
	ds_write2_b32 v136, v9, v5 offset0:228 offset1:244
	ds_write2_b32 v149, v10, v6 offset0:104 offset1:120
	ds_write2_b32 v149, v11, v7 offset0:236 offset1:252
	s_waitcnt lgkmcnt(0)
	ds_read2st64_b32 v[212:213], v137 offset1:1
	v_add_u32_e32 v207, 16, v137
	ds_read2st64_b32 v[214:215], v207 offset0:2 offset1:3
	v_add_u32_e32 v207, 32, v137
	ds_read2st64_b32 v[216:217], v207 offset0:4 offset1:5
	v_add_u32_e32 v207, 48, v137
	ds_read2st64_b32 v[218:219], v207 offset0:6 offset1:7
	v_add_u32_e32 v207, 64, v137
	ds_read2st64_b32 v[220:221], v207 offset0:8 offset1:9
	v_add_u32_e32 v207, 80, v137
	ds_read2st64_b32 v[222:223], v207 offset0:10 offset1:11
	v_add_u32_e32 v207, 96, v137
	ds_read2st64_b32 v[224:225], v207 offset0:12 offset1:13
	v_add_u32_e32 v207, 112, v137
	ds_read2st64_b32 v[226:227], v207 offset0:14 offset1:15
	v_add_u32_e32 v207, 128, v137
	ds_read2st64_b32 v[228:229], v207 offset0:16 offset1:17
	v_add_u32_e32 v207, 144, v137
	ds_read2st64_b32 v[230:231], v207 offset0:18 offset1:19
	v_add_u32_e32 v207, 160, v137
	ds_read2st64_b32 v[232:233], v207 offset0:20 offset1:21
	v_add_u32_e32 v207, 176, v137
	ds_read2st64_b32 v[234:235], v207 offset0:22 offset1:23
	v_add_u32_e32 v207, 192, v137
	ds_read2st64_b32 v[236:237], v207 offset0:24 offset1:25
	v_add_u32_e32 v207, 208, v137
	ds_read2st64_b32 v[238:239], v207 offset0:26 offset1:27
	v_add_u32_e32 v207, 224, v137
	ds_read2st64_b32 v[240:241], v207 offset0:28 offset1:29
	v_add_u32_e32 v207, 240, v137
	ds_read2st64_b32 v[242:243], v207 offset0:30 offset1:31
	s_nop 0
	s_nop 0
	s_waitcnt lgkmcnt(15)
	v_fma_f32 v212, v66, v128, v212
	v_fma_f32 v213, v66, v129, v213
	v_fma_f32 v212, -v68, v129, v212
	v_fma_f32 v213, v68, v128, v213
	v_mov_b64_e32 v[4:5], v[212:213]
	s_nop 0
	v_cvt_pk_bf16_f32 v6, v4, v5
	ds_write_b16 v138, v6
	ds_write_b16_d16_hi v138, v6 offset:128
	s_nop 0
	s_nop 0
	s_waitcnt lgkmcnt(15)
	v_fma_f32 v214, v66, v4, v214
	v_fma_f32 v215, v66, v5, v215
	v_fma_f32 v214, -v68, v5, v214
	v_fma_f32 v215, v68, v4, v215
	v_mov_b64_e32 v[4:5], v[214:215]
	s_nop 0
	v_cvt_pk_bf16_f32 v6, v4, v5
	ds_write_b16 v138, v6 offset:272
	ds_write_b16_d16_hi v138, v6 offset:400
	s_nop 0
	s_nop 0
	s_waitcnt lgkmcnt(15)
	v_fma_f32 v216, v66, v4, v216
	v_fma_f32 v217, v66, v5, v217
	v_fma_f32 v216, -v68, v5, v216
	v_fma_f32 v217, v68, v4, v217
	v_mov_b64_e32 v[4:5], v[216:217]
	s_nop 0
	v_cvt_pk_bf16_f32 v6, v4, v5
	ds_write_b16 v138, v6 offset:544
	ds_write_b16_d16_hi v138, v6 offset:672
	s_nop 0
	s_nop 0
	s_waitcnt lgkmcnt(15)
	v_fma_f32 v218, v66, v4, v218
	v_fma_f32 v219, v66, v5, v219
	v_fma_f32 v218, -v68, v5, v218
	v_fma_f32 v219, v68, v4, v219
	v_mov_b64_e32 v[4:5], v[218:219]
	s_nop 0
	v_cvt_pk_bf16_f32 v6, v4, v5
	ds_write_b16 v138, v6 offset:816
	ds_write_b16_d16_hi v138, v6 offset:944
	s_nop 0
	s_nop 0
	s_waitcnt lgkmcnt(15)
	v_fma_f32 v220, v66, v4, v220
	v_fma_f32 v221, v66, v5, v221
	v_fma_f32 v220, -v68, v5, v220
	v_fma_f32 v221, v68, v4, v221
	v_mov_b64_e32 v[4:5], v[220:221]
	s_nop 0
	v_cvt_pk_bf16_f32 v6, v4, v5
	ds_write_b16 v138, v6 offset:1088
	ds_write_b16_d16_hi v138, v6 offset:1216
	s_nop 0
	s_nop 0
	s_waitcnt lgkmcnt(15)
	v_fma_f32 v222, v66, v4, v222
	v_fma_f32 v223, v66, v5, v223
	v_fma_f32 v222, -v68, v5, v222
	v_fma_f32 v223, v68, v4, v223
	v_mov_b64_e32 v[4:5], v[222:223]
	s_nop 0
	v_cvt_pk_bf16_f32 v6, v4, v5
	ds_write_b16 v138, v6 offset:1360
	ds_write_b16_d16_hi v138, v6 offset:1488
	s_nop 0
	s_nop 0
	s_waitcnt lgkmcnt(15)
	v_fma_f32 v224, v66, v4, v224
	v_fma_f32 v225, v66, v5, v225
	v_fma_f32 v224, -v68, v5, v224
	v_fma_f32 v225, v68, v4, v225
	v_mov_b64_e32 v[4:5], v[224:225]
	s_nop 0
	v_cvt_pk_bf16_f32 v6, v4, v5
	ds_write_b16 v138, v6 offset:1632
	ds_write_b16_d16_hi v138, v6 offset:1760
	s_nop 0
	s_nop 0
	s_waitcnt lgkmcnt(15)
	v_fma_f32 v226, v66, v4, v226
	v_fma_f32 v227, v66, v5, v227
	v_fma_f32 v226, -v68, v5, v226
	v_fma_f32 v227, v68, v4, v227
	v_mov_b64_e32 v[4:5], v[226:227]
	s_nop 0
	v_cvt_pk_bf16_f32 v6, v4, v5
	ds_write_b16 v138, v6 offset:1904
	ds_write_b16_d16_hi v138, v6 offset:2032
	s_nop 0
	s_nop 0
	s_waitcnt lgkmcnt(15)
	v_fma_f32 v228, v66, v4, v228
	v_fma_f32 v229, v66, v5, v229
	v_fma_f32 v228, -v68, v5, v228
	v_fma_f32 v229, v68, v4, v229
	v_mov_b64_e32 v[4:5], v[228:229]
	s_nop 0
	v_cvt_pk_bf16_f32 v6, v4, v5
	ds_write_b16 v138, v6 offset:2176
	ds_write_b16_d16_hi v138, v6 offset:2304
	s_nop 0
	s_nop 0
	s_waitcnt lgkmcnt(15)
	v_fma_f32 v230, v66, v4, v230
	v_fma_f32 v231, v66, v5, v231
	v_fma_f32 v230, -v68, v5, v230
	v_fma_f32 v231, v68, v4, v231
	v_mov_b64_e32 v[4:5], v[230:231]
	s_nop 0
	v_cvt_pk_bf16_f32 v6, v4, v5
	ds_write_b16 v138, v6 offset:2448
	ds_write_b16_d16_hi v138, v6 offset:2576
	s_nop 0
	s_nop 0
	s_waitcnt lgkmcnt(15)
	v_fma_f32 v232, v66, v4, v232
	v_fma_f32 v233, v66, v5, v233
	v_fma_f32 v232, -v68, v5, v232
	v_fma_f32 v233, v68, v4, v233
	v_mov_b64_e32 v[4:5], v[232:233]
	s_nop 0
	v_cvt_pk_bf16_f32 v6, v4, v5
	ds_write_b16 v138, v6 offset:2720
	ds_write_b16_d16_hi v138, v6 offset:2848
	s_nop 0
	s_nop 0
	s_waitcnt lgkmcnt(15)
	v_fma_f32 v234, v66, v4, v234
	v_fma_f32 v235, v66, v5, v235
	v_fma_f32 v234, -v68, v5, v234
	v_fma_f32 v235, v68, v4, v235
	v_mov_b64_e32 v[4:5], v[234:235]
	s_nop 0
	v_cvt_pk_bf16_f32 v6, v4, v5
	ds_write_b16 v138, v6 offset:2992
	ds_write_b16_d16_hi v138, v6 offset:3120
	s_nop 0
	s_nop 0
	s_waitcnt lgkmcnt(15)
	v_fma_f32 v236, v66, v4, v236
	v_fma_f32 v237, v66, v5, v237
	v_fma_f32 v236, -v68, v5, v236
	v_fma_f32 v237, v68, v4, v237
	v_mov_b64_e32 v[4:5], v[236:237]
	s_nop 0
	v_cvt_pk_bf16_f32 v6, v4, v5
	ds_write_b16 v138, v6 offset:3264
	ds_write_b16_d16_hi v138, v6 offset:3392
	s_nop 0
	s_nop 0
	s_waitcnt lgkmcnt(15)
	v_fma_f32 v238, v66, v4, v238
	v_fma_f32 v239, v66, v5, v239
	v_fma_f32 v238, -v68, v5, v238
	v_fma_f32 v239, v68, v4, v239
	v_mov_b64_e32 v[4:5], v[238:239]
	s_nop 0
	v_cvt_pk_bf16_f32 v6, v4, v5
	ds_write_b16 v138, v6 offset:3536
	ds_write_b16_d16_hi v138, v6 offset:3664
	s_nop 0
	s_nop 0
	s_waitcnt lgkmcnt(15)
	v_fma_f32 v240, v66, v4, v240
	v_fma_f32 v241, v66, v5, v241
	v_fma_f32 v240, -v68, v5, v240
	v_fma_f32 v241, v68, v4, v241
	v_mov_b64_e32 v[4:5], v[240:241]
	s_nop 0
	v_cvt_pk_bf16_f32 v6, v4, v5
	ds_write_b16 v138, v6 offset:3808
	ds_write_b16_d16_hi v138, v6 offset:3936
	s_nop 0
	s_nop 0
	s_waitcnt lgkmcnt(15)
	v_fma_f32 v242, v66, v4, v242
	v_fma_f32 v243, v66, v5, v243
	v_fma_f32 v242, -v68, v5, v242
	v_fma_f32 v243, v68, v4, v243
	v_mov_b64_e32 v[128:129], v[242:243]
	s_nop 0
	v_cvt_pk_bf16_f32 v4, v128, v129
	ds_write_b16 v138, v4 offset:4080
	ds_write_b16_d16_hi v138, v4 offset:4208
	s_waitcnt lgkmcnt(0)
	ds_read_b128 v[4:7], v140
	ds_read_b128 v[8:11], v140 offset:64
	s_waitcnt lgkmcnt(1)
	v_mfma_f32_16x16x32_bf16 v[4:7], v[4:7], v[50:53], 0
	ds_read_b128 v[12:15], v140 offset:128
	s_waitcnt lgkmcnt(1)
	v_mfma_f32_16x16x32_bf16 v[4:7], v[8:11], v[46:49], v[4:7]
	ds_read_b128 v[8:11], v140 offset:192
	s_waitcnt lgkmcnt(1)
	v_mfma_f32_16x16x32_bf16 v[4:7], v[12:15], v[42:45], v[4:7]
	s_waitcnt lgkmcnt(0)
	v_mfma_f32_16x16x32_bf16 v[4:7], v[8:11], v[38:41], v[4:7]
	s_nop 7
	v_fma_f32 v4, v144, v145, v4
	v_mul_f32_e32 v8, 0x3d372713, v4
	v_mul_f32_e32 v8, v4, v8
	v_fma_f32 v5, v142, v145, v5
	v_fma_f32 v8, v4, v8, v4
	v_mul_f32_e32 v9, 0x3d372713, v5
	v_mul_f32_e32 v8, 0xbfcc422a, v8
	v_mul_f32_e32 v9, v5, v9
	v_mul_f32_e32 v8, 0x3fb8aa3b, v8
	v_fma_f32 v9, v5, v9, v5
	v_exp_f32_e32 v8, v8
	v_mul_f32_e32 v9, 0xbfcc422a, v9
	v_mul_f32_e32 v9, 0x3fb8aa3b, v9
	v_exp_f32_e32 v9, v9
	v_add_f32_e32 v8, 1.0, v8
	v_rcp_f32_e32 v8, v8
	v_fmac_f32_e32 v7, v131, v145
	v_add_f32_e32 v9, 1.0, v9
	v_rcp_f32_e32 v9, v9
	v_mul_f32_e32 v4, v4, v8
	v_cvt_pk_bf16_f32 v4, v4, v20
	ds_write_b16 v130, v4 offset:25344
	v_mul_f32_e32 v4, v5, v9
	v_fma_f32 v5, v143, v145, v6
	v_mul_f32_e32 v6, 0x3d372713, v5
	v_mul_f32_e32 v8, 0x3d372713, v7
	v_mul_f32_e32 v6, v5, v6
	v_mul_f32_e32 v8, v7, v8
	v_fma_f32 v6, v5, v6, v5
	v_fma_f32 v8, v7, v8, v7
	v_mul_f32_e32 v6, 0xbfcc422a, v6
	v_mul_f32_e32 v8, 0xbfcc422a, v8
	v_mul_f32_e32 v6, 0x3fb8aa3b, v6
	v_mul_f32_e32 v8, 0x3fb8aa3b, v8
	v_exp_f32_e32 v6, v6
	v_exp_f32_e32 v8, v8
	v_cvt_pk_bf16_f32 v4, v4, v20
	ds_write_b16 v130, v4 offset:25872
	v_add_f32_e32 v6, 1.0, v6
	v_add_f32_e32 v4, 1.0, v8
	v_rcp_f32_e32 v6, v6
	v_rcp_f32_e32 v4, v4
	v_mul_f32_e32 v5, v5, v6
	v_mul_f32_e32 v4, v7, v4
	v_cvt_pk_bf16_f32 v5, v5, v20
	ds_write_b16 v130, v5 offset:26400
	v_cvt_pk_bf16_f32 v4, v4, v20
	ds_write_b16 v130, v4 offset:26928
	s_waitcnt lgkmcnt(0)
	s_andn2_b64 vcc, exec, s[46:47]
	s_cbranch_vccnz .LBB0_359
	s_branch .LBB0_399

.LBB0_397:
	v_mfma_f32_16x16x32_bf16 v[62:65], v[58:61], v[30:33], 0
	v_mfma_f32_16x16x32_bf16 v[178:181], v[58:61], v[34:37], 0
	s_nop 7
	ds_write2_b32 v136, v62, v178 offset1:16
	ds_write2_b32 v136, v63, v179 offset0:132 offset1:148
	ds_write2_b32 v149, v64, v180 offset0:8 offset1:24
	ds_write2_b32 v149, v65, v181 offset0:140 offset1:156
	v_mfma_f32_16x16x32_bf16 v[62:65], v[58:61], v[22:25], 0
	v_mfma_f32_16x16x32_bf16 v[178:181], v[58:61], v[26:29], 0
	s_nop 7
	ds_write2_b32 v136, v62, v178 offset0:32 offset1:48
	ds_write2_b32 v136, v63, v179 offset0:164 offset1:180
	ds_write2_b32 v149, v64, v180 offset0:40 offset1:56
	ds_write2_b32 v149, v65, v181 offset0:172 offset1:188
	v_mfma_f32_16x16x32_bf16 v[62:65], v[58:61], v[16:19], 0
	v_mfma_f32_16x16x32_bf16 v[178:181], v[58:61], v[12:15], 0
	s_nop 7
	ds_write2_b32 v136, v62, v178 offset0:64 offset1:80
	ds_write2_b32 v136, v63, v179 offset0:196 offset1:212
	ds_write2_b32 v149, v64, v180 offset0:72 offset1:88
	ds_write2_b32 v149, v65, v181 offset0:204 offset1:220
	v_mfma_f32_16x16x32_bf16 v[62:65], v[58:61], v[8:11], 0
	v_mfma_f32_16x16x32_bf16 v[58:61], v[58:61], v[4:7], 0
	s_nop 7
	ds_write2_b32 v136, v62, v58 offset0:96 offset1:112
	ds_write2_b32 v136, v63, v59 offset0:228 offset1:244
	ds_write2_b32 v149, v64, v60 offset0:104 offset1:120
	ds_write2_b32 v149, v65, v61 offset0:236 offset1:252
	s_waitcnt lgkmcnt(0)
	ds_read2st64_b32 v[212:213], v137 offset1:1
	v_add_u32_e32 v207, 16, v137
	ds_read2st64_b32 v[214:215], v207 offset0:2 offset1:3
	v_add_u32_e32 v207, 32, v137
	ds_read2st64_b32 v[216:217], v207 offset0:4 offset1:5
	v_add_u32_e32 v207, 48, v137
	ds_read2st64_b32 v[218:219], v207 offset0:6 offset1:7
	v_add_u32_e32 v207, 64, v137
	ds_read2st64_b32 v[220:221], v207 offset0:8 offset1:9
	v_add_u32_e32 v207, 80, v137
	ds_read2st64_b32 v[222:223], v207 offset0:10 offset1:11
	v_add_u32_e32 v207, 96, v137
	ds_read2st64_b32 v[224:225], v207 offset0:12 offset1:13
	v_add_u32_e32 v207, 112, v137
	ds_read2st64_b32 v[226:227], v207 offset0:14 offset1:15
	v_add_u32_e32 v207, 128, v137
	ds_read2st64_b32 v[228:229], v207 offset0:16 offset1:17
	v_add_u32_e32 v207, 144, v137
	ds_read2st64_b32 v[230:231], v207 offset0:18 offset1:19
	v_add_u32_e32 v207, 160, v137
	ds_read2st64_b32 v[232:233], v207 offset0:20 offset1:21
	v_add_u32_e32 v207, 176, v137
	ds_read2st64_b32 v[234:235], v207 offset0:22 offset1:23
	v_add_u32_e32 v207, 192, v137
	ds_read2st64_b32 v[236:237], v207 offset0:24 offset1:25
	v_add_u32_e32 v207, 208, v137
	ds_read2st64_b32 v[238:239], v207 offset0:26 offset1:27
	v_add_u32_e32 v207, 224, v137
	ds_read2st64_b32 v[240:241], v207 offset0:28 offset1:29
	v_add_u32_e32 v207, 240, v137
	ds_read2st64_b32 v[242:243], v207 offset0:30 offset1:31
	s_nop 0
	s_nop 0
	s_waitcnt lgkmcnt(15)
	v_fma_f32 v212, v66, v128, v212
	v_fma_f32 v213, v66, v129, v213
	v_fma_f32 v212, -v68, v129, v212
	v_fma_f32 v213, v68, v128, v213
	v_mov_b64_e32 v[58:59], v[212:213]
	s_nop 0
	v_cvt_pk_bf16_f32 v60, v58, v59
	ds_write_b16 v138, v60
	ds_write_b16_d16_hi v138, v60 offset:128
	s_nop 0
	s_nop 0
	s_waitcnt lgkmcnt(15)
	v_fma_f32 v214, v66, v58, v214
	v_fma_f32 v215, v66, v59, v215
	v_fma_f32 v214, -v68, v59, v214
	v_fma_f32 v215, v68, v58, v215
	v_mov_b64_e32 v[58:59], v[214:215]
	s_nop 0
	v_cvt_pk_bf16_f32 v60, v58, v59
	ds_write_b16 v138, v60 offset:272
	ds_write_b16_d16_hi v138, v60 offset:400
	s_nop 0
	s_nop 0
	s_waitcnt lgkmcnt(15)
	v_fma_f32 v216, v66, v58, v216
	v_fma_f32 v217, v66, v59, v217
	v_fma_f32 v216, -v68, v59, v216
	v_fma_f32 v217, v68, v58, v217
	v_mov_b64_e32 v[58:59], v[216:217]
	s_nop 0
	v_cvt_pk_bf16_f32 v60, v58, v59
	ds_write_b16 v138, v60 offset:544
	ds_write_b16_d16_hi v138, v60 offset:672
	s_nop 0
	s_nop 0
	s_waitcnt lgkmcnt(15)
	v_fma_f32 v218, v66, v58, v218
	v_fma_f32 v219, v66, v59, v219
	v_fma_f32 v218, -v68, v59, v218
	v_fma_f32 v219, v68, v58, v219
	v_mov_b64_e32 v[58:59], v[218:219]
	s_nop 0
	v_cvt_pk_bf16_f32 v60, v58, v59
	ds_write_b16 v138, v60 offset:816
	ds_write_b16_d16_hi v138, v60 offset:944
	s_nop 0
	s_nop 0
	s_waitcnt lgkmcnt(15)
	v_fma_f32 v220, v66, v58, v220
	v_fma_f32 v221, v66, v59, v221
	v_fma_f32 v220, -v68, v59, v220
	v_fma_f32 v221, v68, v58, v221
	v_mov_b64_e32 v[58:59], v[220:221]
	s_nop 0
	v_cvt_pk_bf16_f32 v60, v58, v59
	ds_write_b16 v138, v60 offset:1088
	ds_write_b16_d16_hi v138, v60 offset:1216
	s_nop 0
	s_nop 0
	s_waitcnt lgkmcnt(15)
	v_fma_f32 v222, v66, v58, v222
	v_fma_f32 v223, v66, v59, v223
	v_fma_f32 v222, -v68, v59, v222
	v_fma_f32 v223, v68, v58, v223
	v_mov_b64_e32 v[58:59], v[222:223]
	s_nop 0
	v_cvt_pk_bf16_f32 v60, v58, v59
	ds_write_b16 v138, v60 offset:1360
	ds_write_b16_d16_hi v138, v60 offset:1488
	s_nop 0
	s_nop 0
	s_waitcnt lgkmcnt(15)
	v_fma_f32 v224, v66, v58, v224
	v_fma_f32 v225, v66, v59, v225
	v_fma_f32 v224, -v68, v59, v224
	v_fma_f32 v225, v68, v58, v225
	v_mov_b64_e32 v[58:59], v[224:225]
	s_nop 0
	v_cvt_pk_bf16_f32 v60, v58, v59
	ds_write_b16 v138, v60 offset:1632
	ds_write_b16_d16_hi v138, v60 offset:1760
	s_nop 0
	s_nop 0
	s_waitcnt lgkmcnt(15)
	v_fma_f32 v226, v66, v58, v226
	v_fma_f32 v227, v66, v59, v227
	v_fma_f32 v226, -v68, v59, v226
	v_fma_f32 v227, v68, v58, v227
	v_mov_b64_e32 v[58:59], v[226:227]
	s_nop 0
	v_cvt_pk_bf16_f32 v60, v58, v59
	ds_write_b16 v138, v60 offset:1904
	ds_write_b16_d16_hi v138, v60 offset:2032
	s_nop 0
	s_nop 0
	s_waitcnt lgkmcnt(15)
	v_fma_f32 v228, v66, v58, v228
	v_fma_f32 v229, v66, v59, v229
	v_fma_f32 v228, -v68, v59, v228
	v_fma_f32 v229, v68, v58, v229
	v_mov_b64_e32 v[58:59], v[228:229]
	s_nop 0
	v_cvt_pk_bf16_f32 v60, v58, v59
	ds_write_b16 v138, v60 offset:2176
	ds_write_b16_d16_hi v138, v60 offset:2304
	s_nop 0
	s_nop 0
	s_waitcnt lgkmcnt(15)
	v_fma_f32 v230, v66, v58, v230
	v_fma_f32 v231, v66, v59, v231
	v_fma_f32 v230, -v68, v59, v230
	v_fma_f32 v231, v68, v58, v231
	v_mov_b64_e32 v[58:59], v[230:231]
	s_nop 0
	v_cvt_pk_bf16_f32 v60, v58, v59
	ds_write_b16 v138, v60 offset:2448
	ds_write_b16_d16_hi v138, v60 offset:2576
	s_nop 0
	s_nop 0
	s_waitcnt lgkmcnt(15)
	v_fma_f32 v232, v66, v58, v232
	v_fma_f32 v233, v66, v59, v233
	v_fma_f32 v232, -v68, v59, v232
	v_fma_f32 v233, v68, v58, v233
	v_mov_b64_e32 v[58:59], v[232:233]
	s_nop 0
	v_cvt_pk_bf16_f32 v60, v58, v59
	ds_write_b16 v138, v60 offset:2720
	ds_write_b16_d16_hi v138, v60 offset:2848
	s_nop 0
	s_nop 0
	s_waitcnt lgkmcnt(15)
	v_fma_f32 v234, v66, v58, v234
	v_fma_f32 v235, v66, v59, v235
	v_fma_f32 v234, -v68, v59, v234
	v_fma_f32 v235, v68, v58, v235
	v_mov_b64_e32 v[58:59], v[234:235]
	s_nop 0
	v_cvt_pk_bf16_f32 v60, v58, v59
	ds_write_b16 v138, v60 offset:2992
	ds_write_b16_d16_hi v138, v60 offset:3120
	s_nop 0
	s_nop 0
	s_waitcnt lgkmcnt(15)
	v_fma_f32 v236, v66, v58, v236
	v_fma_f32 v237, v66, v59, v237
	v_fma_f32 v236, -v68, v59, v236
	v_fma_f32 v237, v68, v58, v237
	v_mov_b64_e32 v[58:59], v[236:237]
	s_nop 0
	v_cvt_pk_bf16_f32 v60, v58, v59
	ds_write_b16 v138, v60 offset:3264
	ds_write_b16_d16_hi v138, v60 offset:3392
	s_nop 0
	s_nop 0
	s_waitcnt lgkmcnt(15)
	v_fma_f32 v238, v66, v58, v238
	v_fma_f32 v239, v66, v59, v239
	v_fma_f32 v238, -v68, v59, v238
	v_fma_f32 v239, v68, v58, v239
	v_mov_b64_e32 v[58:59], v[238:239]
	s_nop 0
	v_cvt_pk_bf16_f32 v60, v58, v59
	ds_write_b16 v138, v60 offset:3536
	ds_write_b16_d16_hi v138, v60 offset:3664
	s_nop 0
	s_nop 0
	s_waitcnt lgkmcnt(15)
	v_fma_f32 v240, v66, v58, v240
	v_fma_f32 v241, v66, v59, v241
	v_fma_f32 v240, -v68, v59, v240
	v_fma_f32 v241, v68, v58, v241
	v_mov_b64_e32 v[58:59], v[240:241]
	s_nop 0
	v_cvt_pk_bf16_f32 v60, v58, v59
	ds_write_b16 v138, v60 offset:3808
	ds_write_b16_d16_hi v138, v60 offset:3936
	s_nop 0
	s_nop 0
	s_waitcnt lgkmcnt(15)
	v_fma_f32 v242, v66, v58, v242
	v_fma_f32 v243, v66, v59, v243
	v_fma_f32 v242, -v68, v59, v242
	v_fma_f32 v243, v68, v58, v243
	v_mov_b64_e32 v[128:129], v[242:243]
	s_nop 0
	v_cvt_pk_bf16_f32 v58, v128, v129
	ds_write_b16 v138, v58 offset:4080
	ds_write_b16_d16_hi v138, v58 offset:4208
	s_waitcnt lgkmcnt(0)
	ds_read_b128 v[58:61], v140
	ds_read_b128 v[62:65], v140 offset:64
	s_waitcnt lgkmcnt(1)
	v_mfma_f32_16x16x32_bf16 v[58:61], v[58:61], v[50:53], 0
	s_waitcnt lgkmcnt(0)
	v_mfma_f32_16x16x32_bf16 v[58:61], v[62:65], v[46:49], v[58:61]
	ds_read_b128 v[62:65], v140 offset:128
	s_waitcnt lgkmcnt(0)
	v_mfma_f32_16x16x32_bf16 v[58:61], v[62:65], v[42:45], v[58:61]
	ds_read_b128 v[62:65], v140 offset:192
	s_waitcnt lgkmcnt(0)
	v_mfma_f32_16x16x32_bf16 v[58:61], v[62:65], v[38:41], v[58:61]
	s_nop 7
	v_fma_f32 v58, v162, v145, v58
	v_mul_f32_e32 v62, 0x3d372713, v58
	v_mul_f32_e32 v62, v58, v62
	v_fma_f32 v62, v58, v62, v58
	v_mul_f32_e32 v62, 0xbfcc422a, v62
	v_mul_f32_e32 v62, 0x3fb8aa3b, v62
	v_exp_f32_e32 v62, v62
	v_fmac_f32_e32 v61, v146, v145
	v_add_f32_e32 v62, 1.0, v62
	v_rcp_f32_e32 v62, v62
	s_nop 0
	v_mul_f32_e32 v58, v58, v62
	v_cvt_pk_bf16_f32 v58, v58, v20
	ds_write_b16 v130, v58 offset:16896
	v_fma_f32 v58, v148, v145, v59
	v_mul_f32_e32 v59, 0x3d372713, v58
	v_mul_f32_e32 v59, v58, v59
	v_fma_f32 v59, v58, v59, v58
	v_mul_f32_e32 v59, 0xbfcc422a, v59
	v_mul_f32_e32 v59, 0x3fb8aa3b, v59
	v_exp_f32_e32 v59, v59
	s_nop 0
	v_add_f32_e32 v59, 1.0, v59
	v_rcp_f32_e32 v59, v59
	s_nop 0
	v_mul_f32_e32 v58, v58, v59
	v_cvt_pk_bf16_f32 v58, v58, v20
	ds_write_b16 v130, v58 offset:17424
	v_fma_f32 v58, v147, v145, v60
	v_mul_f32_e32 v59, 0x3d372713, v58
	v_mul_f32_e32 v59, v58, v59
	v_fma_f32 v59, v58, v59, v58
	v_mul_f32_e32 v59, 0xbfcc422a, v59
	v_mul_f32_e32 v59, 0x3fb8aa3b, v59
	v_exp_f32_e32 v59, v59
	s_nop 0
	v_add_f32_e32 v59, 1.0, v59
	v_rcp_f32_e32 v59, v59
	s_nop 0
	v_mul_f32_e32 v58, v58, v59
	v_cvt_pk_bf16_f32 v58, v58, v20
	ds_write_b16 v130, v58 offset:17952
	v_mul_f32_e32 v58, 0x3d372713, v61
	v_mul_f32_e32 v58, v61, v58
	v_fma_f32 v58, v61, v58, v61
	v_mul_f32_e32 v58, 0xbfcc422a, v58
	v_mul_f32_e32 v58, 0x3fb8aa3b, v58
	v_exp_f32_e32 v58, v58
	s_nop 0
	v_add_f32_e32 v58, 1.0, v58
	v_rcp_f32_e32 v58, v58
	s_nop 0
	v_mul_f32_e32 v58, v61, v58
	v_cvt_pk_bf16_f32 v58, v58, v20
	ds_write_b16 v130, v58 offset:18480
	s_waitcnt lgkmcnt(0)
	s_and_b64 vcc, exec, s[38:39]
	s_cbranch_vccz .LBB0_395

.LBB0_517:
	v_lshl_or_b32 v38, v40, 4, v76
	s_waitcnt vmcnt(4)
	v_mfma_f32_16x16x32_bf16 v[168:171], v[66:69], v[30:33], 0
	v_ashrrev_i32_e32 v39, 31, v38
	v_add_u32_e32 v154, v139, v130
	v_lshlrev_b64 v[38:39], 8, v[38:39]
	v_mfma_f32_16x16x32_bf16 v[172:175], v[66:69], v[34:37], 0
	v_ashrrev_i32_e32 v155, 31, v154
	v_lshl_add_u64 v[38:39], v[88:89], 0, v[38:39]
	v_lshl_add_u64 v[154:155], v[154:155], 2, s[52:53]
	v_add_u32_e32 v165, 0x400, v140
	s_waitcnt vmcnt(3)
	v_lshlrev_b32_e32 v188, 16, v41
	s_waitcnt vmcnt(2)
	v_lshlrev_b32_e32 v187, 16, v42
	s_waitcnt vmcnt(1)
	v_lshlrev_b32_e32 v186, 16, v43
	s_waitcnt vmcnt(0)
	v_lshlrev_b32_e32 v185, 16, v44
	global_load_dwordx4 v[50:53], v[38:39], off
	global_load_dwordx4 v[46:49], v[38:39], off offset:64
	global_load_dwordx4 v[42:45], v[38:39], off offset:128
	s_nop 0
	global_load_dwordx4 v[38:41], v[38:39], off offset:192
	v_cndmask_b32_e64 v129, v3, v1, s[8:9]
	global_load_dword v149, v[154:155], off
	ds_write2_b32 v140, v168, v172 offset1:16
	ds_write2_b32 v140, v169, v173 offset0:132 offset1:148
	ds_write2_b32 v165, v170, v174 offset0:8 offset1:24
	ds_write2_b32 v165, v171, v175 offset0:140 offset1:156
	v_mfma_f32_16x16x32_bf16 v[168:171], v[66:69], v[22:25], 0
	v_cndmask_b32_e64 v155, v73, v71, s[8:9]
	v_cndmask_b32_e64 v154, v72, v70, s[8:9]
	v_mov_b32_e32 v132, v129
	v_mfma_f32_16x16x32_bf16 v[172:175], v[66:69], v[26:29], 0
	s_nop 7
	ds_write2_b32 v140, v168, v172 offset0:32 offset1:48
	ds_write2_b32 v140, v169, v173 offset0:164 offset1:180
	ds_write2_b32 v165, v170, v174 offset0:40 offset1:56
	ds_write2_b32 v165, v171, v175 offset0:172 offset1:188
	v_mfma_f32_16x16x32_bf16 v[168:171], v[66:69], v[16:19], 0
	v_cndmask_b32_e64 v128, v2, v0, s[8:9]
	v_add_u32_e32 v167, 32, v141
	v_add_u32_e32 v180, 0xf0, v141
	v_mfma_f32_16x16x32_bf16 v[172:175], v[66:69], v[12:15], 0
	s_nop 7
	ds_write2_b32 v140, v168, v172 offset0:64 offset1:80
	ds_write2_b32 v140, v169, v173 offset0:196 offset1:212
	ds_write2_b32 v165, v170, v174 offset0:72 offset1:88
	ds_write2_b32 v165, v171, v175 offset0:204 offset1:220
	v_mfma_f32_16x16x32_bf16 v[168:171], v[66:69], v[8:11], 0
	v_lshl_add_u32 v130, v130, 1, v143
	s_and_b64 vcc, exec, s[38:39]
	v_mfma_f32_16x16x32_bf16 v[66:69], v[66:69], v[4:7], 0
	s_nop 7
	ds_write2_b32 v140, v168, v66 offset0:96 offset1:112
	ds_write2_b32 v140, v169, v67 offset0:228 offset1:244
	ds_write2_b32 v165, v170, v68 offset0:104 offset1:120
	ds_write2_b32 v165, v171, v69 offset0:236 offset1:252
	s_waitcnt lgkmcnt(0)
	ds_read2st64_b32 v[216:217], v141 offset1:1
	v_add_u32_e32 v207, 16, v141
	ds_read2st64_b32 v[218:219], v207 offset0:2 offset1:3
	v_add_u32_e32 v207, 32, v141
	ds_read2st64_b32 v[220:221], v207 offset0:4 offset1:5
	v_add_u32_e32 v207, 48, v141
	ds_read2st64_b32 v[222:223], v207 offset0:6 offset1:7
	v_add_u32_e32 v207, 64, v141
	ds_read2st64_b32 v[224:225], v207 offset0:8 offset1:9
	v_add_u32_e32 v207, 80, v141
	ds_read2st64_b32 v[226:227], v207 offset0:10 offset1:11
	v_add_u32_e32 v207, 96, v141
	ds_read2st64_b32 v[228:229], v207 offset0:12 offset1:13
	v_add_u32_e32 v207, 112, v141
	ds_read2st64_b32 v[230:231], v207 offset0:14 offset1:15
	v_add_u32_e32 v207, 128, v141
	ds_read2st64_b32 v[232:233], v207 offset0:16 offset1:17
	v_add_u32_e32 v207, 144, v141
	ds_read2st64_b32 v[234:235], v207 offset0:18 offset1:19
	v_add_u32_e32 v207, 160, v141
	ds_read2st64_b32 v[236:237], v207 offset0:20 offset1:21
	v_add_u32_e32 v207, 176, v141
	ds_read2st64_b32 v[238:239], v207 offset0:22 offset1:23
	v_add_u32_e32 v207, 192, v141
	ds_read2st64_b32 v[240:241], v207 offset0:24 offset1:25
	v_add_u32_e32 v207, 208, v141
	ds_read2st64_b32 v[242:243], v207 offset0:26 offset1:27
	v_add_u32_e32 v207, 224, v141
	ds_read2st64_b32 v[244:245], v207 offset0:28 offset1:29
	v_add_u32_e32 v207, 240, v141
	ds_read2st64_b32 v[246:247], v207 offset0:30 offset1:31
	s_waitcnt lgkmcnt(15)
	v_fma_f32 v216, v128, v154, v216
	v_fma_f32 v217, v128, v155, v217
	v_fma_f32 v216, -v132, v155, v216
	v_fma_f32 v217, v132, v154, v217
	v_mov_b64_e32 v[154:155], v[216:217]
	v_mov_b32_e32 v66, v128
	v_cvt_pk_bf16_f32 v156, v154, v155
	ds_write_b16 v142, v156
	ds_write_b16_d16_hi v142, v156 offset:128
	s_waitcnt lgkmcnt(15)
	v_fma_f32 v218, v128, v154, v218
	v_fma_f32 v219, v128, v155, v219
	v_fma_f32 v218, -v132, v155, v218
	v_fma_f32 v219, v132, v154, v219
	v_mov_b64_e32 v[154:155], v[218:219]
	v_mov_b32_e32 v67, v128
	v_cvt_pk_bf16_f32 v156, v154, v155
	ds_write_b16 v142, v156 offset:272
	ds_write_b16_d16_hi v142, v156 offset:400
	s_waitcnt lgkmcnt(15)
	v_fma_f32 v220, v128, v154, v220
	v_fma_f32 v221, v128, v155, v221
	v_fma_f32 v220, -v132, v155, v220
	v_fma_f32 v221, v132, v154, v221
	v_mov_b64_e32 v[154:155], v[220:221]
	v_add_u32_e32 v168, 48, v141
	v_cvt_pk_bf16_f32 v156, v154, v155
	ds_write_b16 v142, v156 offset:544
	ds_write_b16_d16_hi v142, v156 offset:672
	s_waitcnt lgkmcnt(15)
	v_fma_f32 v222, v128, v154, v222
	v_fma_f32 v223, v128, v155, v223
	v_fma_f32 v222, -v132, v155, v222
	v_fma_f32 v223, v132, v154, v223
	v_mov_b64_e32 v[154:155], v[222:223]
	v_add_u32_e32 v169, 64, v141
	v_cvt_pk_bf16_f32 v156, v154, v155
	ds_write_b16 v142, v156 offset:816
	ds_write_b16_d16_hi v142, v156 offset:944
	s_waitcnt lgkmcnt(15)
	v_fma_f32 v224, v128, v154, v224
	v_fma_f32 v225, v128, v155, v225
	v_fma_f32 v224, -v132, v155, v224
	v_fma_f32 v225, v132, v154, v225
	v_mov_b64_e32 v[154:155], v[224:225]
	v_add_u32_e32 v170, 0x50, v141
	v_cvt_pk_bf16_f32 v156, v154, v155
	ds_write_b16 v142, v156 offset:1088
	ds_write_b16_d16_hi v142, v156 offset:1216
	s_waitcnt lgkmcnt(15)
	v_fma_f32 v226, v128, v154, v226
	v_fma_f32 v227, v128, v155, v227
	v_fma_f32 v226, -v132, v155, v226
	v_fma_f32 v227, v132, v154, v227
	v_mov_b64_e32 v[154:155], v[226:227]
	v_add_u32_e32 v171, 0x60, v141
	v_cvt_pk_bf16_f32 v156, v154, v155
	ds_write_b16 v142, v156 offset:1360
	ds_write_b16_d16_hi v142, v156 offset:1488
	s_waitcnt lgkmcnt(15)
	v_fma_f32 v228, v128, v154, v228
	v_fma_f32 v229, v128, v155, v229
	v_fma_f32 v228, -v132, v155, v228
	v_fma_f32 v229, v132, v154, v229
	v_mov_b64_e32 v[154:155], v[228:229]
	v_add_u32_e32 v172, 0x70, v141
	v_cvt_pk_bf16_f32 v156, v154, v155
	ds_write_b16 v142, v156 offset:1632
	ds_write_b16_d16_hi v142, v156 offset:1760
	s_waitcnt lgkmcnt(15)
	v_fma_f32 v230, v128, v154, v230
	v_fma_f32 v231, v128, v155, v231
	v_fma_f32 v230, -v132, v155, v230
	v_fma_f32 v231, v132, v154, v231
	v_mov_b64_e32 v[154:155], v[230:231]
	v_add_u32_e32 v173, 0x80, v141
	v_cvt_pk_bf16_f32 v156, v154, v155
	ds_write_b16 v142, v156 offset:1904
	ds_write_b16_d16_hi v142, v156 offset:2032
	s_waitcnt lgkmcnt(15)
	v_fma_f32 v232, v128, v154, v232
	v_fma_f32 v233, v128, v155, v233
	v_fma_f32 v232, -v132, v155, v232
	v_fma_f32 v233, v132, v154, v233
	v_mov_b64_e32 v[154:155], v[232:233]
	v_add_u32_e32 v174, 0x90, v141
	v_cvt_pk_bf16_f32 v156, v154, v155
	ds_write_b16 v142, v156 offset:2176
	ds_write_b16_d16_hi v142, v156 offset:2304
	s_waitcnt lgkmcnt(15)
	v_fma_f32 v234, v128, v154, v234
	v_fma_f32 v235, v128, v155, v235
	v_fma_f32 v234, -v132, v155, v234
	v_fma_f32 v235, v132, v154, v235
	v_mov_b64_e32 v[154:155], v[234:235]
	v_add_u32_e32 v175, 0xa0, v141
	v_cvt_pk_bf16_f32 v156, v154, v155
	ds_write_b16 v142, v156 offset:2448
	ds_write_b16_d16_hi v142, v156 offset:2576
	s_waitcnt lgkmcnt(15)
	v_fma_f32 v236, v128, v154, v236
	v_fma_f32 v237, v128, v155, v237
	v_fma_f32 v236, -v132, v155, v236
	v_fma_f32 v237, v132, v154, v237
	v_mov_b64_e32 v[154:155], v[236:237]
	v_add_u32_e32 v176, 0xb0, v141
	v_cvt_pk_bf16_f32 v156, v154, v155
	ds_write_b16 v142, v156 offset:2720
	ds_write_b16_d16_hi v142, v156 offset:2848
	s_waitcnt lgkmcnt(15)
	v_fma_f32 v238, v128, v154, v238
	v_fma_f32 v239, v128, v155, v239
	v_fma_f32 v238, -v132, v155, v238
	v_fma_f32 v239, v132, v154, v239
	v_mov_b64_e32 v[154:155], v[238:239]
	v_add_u32_e32 v177, 0xc0, v141
	v_cvt_pk_bf16_f32 v156, v154, v155
	ds_write_b16 v142, v156 offset:2992
	ds_write_b16_d16_hi v142, v156 offset:3120
	s_waitcnt lgkmcnt(15)
	v_fma_f32 v240, v128, v154, v240
	v_fma_f32 v241, v128, v155, v241
	v_fma_f32 v240, -v132, v155, v240
	v_fma_f32 v241, v132, v154, v241
	v_mov_b64_e32 v[154:155], v[240:241]
	v_add_u32_e32 v178, 0xd0, v141
	v_cvt_pk_bf16_f32 v156, v154, v155
	ds_write_b16 v142, v156 offset:3264
	ds_write_b16_d16_hi v142, v156 offset:3392
	s_waitcnt lgkmcnt(15)
	v_fma_f32 v242, v128, v154, v242
	v_fma_f32 v243, v128, v155, v243
	v_fma_f32 v242, -v132, v155, v242
	v_fma_f32 v243, v132, v154, v243
	v_mov_b64_e32 v[154:155], v[242:243]
	v_add_u32_e32 v179, 0xe0, v141
	v_cvt_pk_bf16_f32 v156, v154, v155
	ds_write_b16 v142, v156 offset:3536
	ds_write_b16_d16_hi v142, v156 offset:3664
	s_waitcnt lgkmcnt(15)
	v_fma_f32 v244, v128, v154, v244
	v_fma_f32 v245, v128, v155, v245
	v_fma_f32 v244, -v132, v155, v244
	v_fma_f32 v245, v132, v154, v245
	v_mov_b64_e32 v[154:155], v[244:245]
	v_mov_b32_e32 v68, v129
	v_cvt_pk_bf16_f32 v156, v154, v155
	ds_write_b16 v142, v156 offset:3808
	ds_write_b16_d16_hi v142, v156 offset:3936
	v_mov_b32_e32 v69, v129
	s_waitcnt lgkmcnt(15)
	v_fma_f32 v246, v128, v154, v246
	v_fma_f32 v247, v128, v155, v247
	v_fma_f32 v246, -v132, v155, v246
	v_fma_f32 v247, v132, v154, v247
	v_mov_b64_e32 v[128:129], v[246:247]
	s_nop 0
	v_cvt_pk_bf16_f32 v132, v128, v129
	ds_write_b16 v142, v132 offset:4080
	ds_write_b16_d16_hi v142, v132 offset:4208
	s_waitcnt lgkmcnt(0)
	ds_read_b128 v[208:211], v144
	ds_read_b128 v[212:215], v144 offset:64
	s_waitcnt vmcnt(4) lgkmcnt(1)
	v_mfma_f32_16x16x32_bf16 v[208:211], v[208:211], v[50:53], 0
	s_waitcnt vmcnt(3) lgkmcnt(0)
	v_mfma_f32_16x16x32_bf16 v[208:211], v[212:215], v[46:49], v[208:211]
	ds_read_b128 v[212:215], v144 offset:128
	s_waitcnt vmcnt(2) lgkmcnt(0)
	v_mfma_f32_16x16x32_bf16 v[208:211], v[212:215], v[42:45], v[208:211]
	ds_read_b128 v[212:215], v144 offset:192
	s_waitcnt vmcnt(1) lgkmcnt(0)
	v_mfma_f32_16x16x32_bf16 v[208:211], v[212:215], v[38:41], v[208:211]
	s_waitcnt vmcnt(0)
	s_nop 6
	v_fma_f32 v132, v149, v188, v208
	v_mul_f32_e32 v154, 0x3d372713, v132
	v_mul_f32_e32 v154, v132, v154
	v_fma_f32 v154, v132, v154, v132
	v_mul_f32_e32 v154, 0xbfcc422a, v154
	v_mul_f32_e32 v154, 0x3fb8aa3b, v154
	v_exp_f32_e32 v154, v154
	v_fmac_f32_e32 v211, v149, v185
	v_add_f32_e32 v154, 1.0, v154
	v_rcp_f32_e32 v154, v154
	s_nop 0
	v_mul_f32_e32 v132, v132, v154
	v_cvt_pk_bf16_f32 v132, v132, v20
	ds_write_b16 v130, v132
	v_fma_f32 v132, v149, v187, v209
	v_mul_f32_e32 v154, 0x3d372713, v132
	v_mul_f32_e32 v154, v132, v154
	v_fma_f32 v154, v132, v154, v132
	v_mul_f32_e32 v154, 0xbfcc422a, v154
	v_mul_f32_e32 v154, 0x3fb8aa3b, v154
	v_exp_f32_e32 v154, v154
	s_nop 0
	v_add_f32_e32 v154, 1.0, v154
	v_rcp_f32_e32 v154, v154
	s_nop 0
	v_mul_f32_e32 v132, v132, v154
	v_cvt_pk_bf16_f32 v132, v132, v20
	ds_write_b16 v130, v132 offset:528
	v_fma_f32 v132, v149, v186, v210
	v_mul_f32_e32 v154, 0x3d372713, v132
	v_mul_f32_e32 v154, v132, v154
	v_fma_f32 v154, v132, v154, v132
	v_mul_f32_e32 v154, 0xbfcc422a, v154
	v_mul_f32_e32 v154, 0x3fb8aa3b, v154
	v_exp_f32_e32 v154, v154
	s_nop 0
	v_add_f32_e32 v154, 1.0, v154
	v_rcp_f32_e32 v154, v154
	s_nop 0
	v_mul_f32_e32 v132, v132, v154
	v_cvt_pk_bf16_f32 v132, v132, v20
	ds_write_b16 v130, v132 offset:1056
	v_mul_f32_e32 v132, 0x3d372713, v211
	v_mul_f32_e32 v132, v211, v132
	v_fma_f32 v132, v211, v132, v211
	v_mul_f32_e32 v132, 0xbfcc422a, v132
	v_mul_f32_e32 v132, 0x3fb8aa3b, v132
	v_exp_f32_e32 v132, v132
	s_nop 0
	v_add_f32_e32 v132, 1.0, v132
	v_rcp_f32_e32 v132, v132
	s_nop 0
	v_mul_f32_e32 v132, v211, v132
	v_cvt_pk_bf16_f32 v132, v132, v20
	ds_write_b16 v130, v132 offset:1584
	s_waitcnt lgkmcnt(0)
	s_cbranch_vccnz .LBB0_521
	v_mfma_f32_16x16x32_bf16 v[186:189], v[62:65], v[30:33], 0
	v_mfma_f32_16x16x32_bf16 v[208:211], v[62:65], v[34:37], 0
	s_nop 7
	ds_write2_b32 v140, v186, v208 offset1:16
	ds_write2_b32 v140, v187, v209 offset0:132 offset1:148
	ds_write2_b32 v165, v188, v210 offset0:8 offset1:24
	ds_write2_b32 v165, v189, v211 offset0:140 offset1:156
	v_mfma_f32_16x16x32_bf16 v[186:189], v[62:65], v[22:25], 0
	v_mfma_f32_16x16x32_bf16 v[208:211], v[62:65], v[26:29], 0
	s_nop 7
	ds_write2_b32 v140, v186, v208 offset0:32 offset1:48
	ds_write2_b32 v140, v187, v209 offset0:164 offset1:180
	ds_write2_b32 v165, v188, v210 offset0:40 offset1:56
	ds_write2_b32 v165, v189, v211 offset0:172 offset1:188
	v_mfma_f32_16x16x32_bf16 v[186:189], v[62:65], v[16:19], 0
	v_mfma_f32_16x16x32_bf16 v[208:211], v[62:65], v[12:15], 0
	s_nop 7
	ds_write2_b32 v140, v186, v208 offset0:64 offset1:80
	ds_write2_b32 v140, v187, v209 offset0:196 offset1:212
	ds_write2_b32 v165, v188, v210 offset0:72 offset1:88
	ds_write2_b32 v165, v189, v211 offset0:204 offset1:220
	v_mfma_f32_16x16x32_bf16 v[186:189], v[62:65], v[8:11], 0
	v_mfma_f32_16x16x32_bf16 v[62:65], v[62:65], v[4:7], 0
	s_nop 7
	ds_write2_b32 v140, v186, v62 offset0:96 offset1:112
	ds_write2_b32 v140, v187, v63 offset0:228 offset1:244
	ds_write2_b32 v165, v188, v64 offset0:104 offset1:120
	ds_write2_b32 v165, v189, v65 offset0:236 offset1:252
	s_waitcnt lgkmcnt(0)
	ds_read2st64_b32 v[216:217], v141 offset1:1
	v_add_u32_e32 v207, 16, v141
	ds_read2st64_b32 v[218:219], v207 offset0:2 offset1:3
	v_add_u32_e32 v207, 32, v141
	ds_read2st64_b32 v[220:221], v207 offset0:4 offset1:5
	v_add_u32_e32 v207, 48, v141
	ds_read2st64_b32 v[222:223], v207 offset0:6 offset1:7
	v_add_u32_e32 v207, 64, v141
	ds_read2st64_b32 v[224:225], v207 offset0:8 offset1:9
	v_add_u32_e32 v207, 80, v141
	ds_read2st64_b32 v[226:227], v207 offset0:10 offset1:11
	v_add_u32_e32 v207, 96, v141
	ds_read2st64_b32 v[228:229], v207 offset0:12 offset1:13
	v_add_u32_e32 v207, 112, v141
	ds_read2st64_b32 v[230:231], v207 offset0:14 offset1:15
	v_add_u32_e32 v207, 128, v141
	ds_read2st64_b32 v[232:233], v207 offset0:16 offset1:17
	v_add_u32_e32 v207, 144, v141
	ds_read2st64_b32 v[234:235], v207 offset0:18 offset1:19
	v_add_u32_e32 v207, 160, v141
	ds_read2st64_b32 v[236:237], v207 offset0:20 offset1:21
	v_add_u32_e32 v207, 176, v141
	ds_read2st64_b32 v[238:239], v207 offset0:22 offset1:23
	v_add_u32_e32 v207, 192, v141
	ds_read2st64_b32 v[240:241], v207 offset0:24 offset1:25
	v_add_u32_e32 v207, 208, v141
	ds_read2st64_b32 v[242:243], v207 offset0:26 offset1:27
	v_add_u32_e32 v207, 224, v141
	ds_read2st64_b32 v[244:245], v207 offset0:28 offset1:29
	v_add_u32_e32 v207, 240, v141
	ds_read2st64_b32 v[246:247], v207 offset0:30 offset1:31
	s_nop 0
	s_nop 0
	s_waitcnt lgkmcnt(15)
	v_fma_f32 v216, v66, v128, v216
	v_fma_f32 v217, v67, v129, v217
	v_fma_f32 v216, -v69, v129, v216
	v_fma_f32 v217, v68, v128, v217
	v_mov_b64_e32 v[62:63], v[216:217]
	s_nop 0
	v_cvt_pk_bf16_f32 v64, v62, v63
	ds_write_b16 v142, v64
	ds_write_b16_d16_hi v142, v64 offset:128
	s_nop 0
	s_nop 0
	s_waitcnt lgkmcnt(15)
	v_fma_f32 v218, v66, v62, v218
	v_fma_f32 v219, v67, v63, v219
	v_fma_f32 v218, -v69, v63, v218
	v_fma_f32 v219, v68, v62, v219
	v_mov_b64_e32 v[62:63], v[218:219]
	s_nop 0
	v_cvt_pk_bf16_f32 v64, v62, v63
	ds_write_b16 v142, v64 offset:272
	ds_write_b16_d16_hi v142, v64 offset:400
	s_nop 0
	s_nop 0
	s_waitcnt lgkmcnt(15)
	v_fma_f32 v220, v66, v62, v220
	v_fma_f32 v221, v67, v63, v221
	v_fma_f32 v220, -v69, v63, v220
	v_fma_f32 v221, v68, v62, v221
	v_mov_b64_e32 v[62:63], v[220:221]
	s_nop 0
	v_cvt_pk_bf16_f32 v64, v62, v63
	ds_write_b16 v142, v64 offset:544
	ds_write_b16_d16_hi v142, v64 offset:672
	s_nop 0
	s_nop 0
	s_waitcnt lgkmcnt(15)
	v_fma_f32 v222, v66, v62, v222
	v_fma_f32 v223, v67, v63, v223
	v_fma_f32 v222, -v69, v63, v222
	v_fma_f32 v223, v68, v62, v223
	v_mov_b64_e32 v[62:63], v[222:223]
	s_nop 0
	v_cvt_pk_bf16_f32 v64, v62, v63
	ds_write_b16 v142, v64 offset:816
	ds_write_b16_d16_hi v142, v64 offset:944
	s_nop 0
	s_nop 0
	s_waitcnt lgkmcnt(15)
	v_fma_f32 v224, v66, v62, v224
	v_fma_f32 v225, v67, v63, v225
	v_fma_f32 v224, -v69, v63, v224
	v_fma_f32 v225, v68, v62, v225
	v_mov_b64_e32 v[62:63], v[224:225]
	s_nop 0
	v_cvt_pk_bf16_f32 v64, v62, v63
	ds_write_b16 v142, v64 offset:1088
	ds_write_b16_d16_hi v142, v64 offset:1216
	s_nop 0
	s_nop 0
	s_waitcnt lgkmcnt(15)
	v_fma_f32 v226, v66, v62, v226
	v_fma_f32 v227, v67, v63, v227
	v_fma_f32 v226, -v69, v63, v226
	v_fma_f32 v227, v68, v62, v227
	v_mov_b64_e32 v[62:63], v[226:227]
	s_nop 0
	v_cvt_pk_bf16_f32 v64, v62, v63
	ds_write_b16 v142, v64 offset:1360
	ds_write_b16_d16_hi v142, v64 offset:1488
	s_nop 0
	s_nop 0
	s_waitcnt lgkmcnt(15)
	v_fma_f32 v228, v66, v62, v228
	v_fma_f32 v229, v67, v63, v229
	v_fma_f32 v228, -v69, v63, v228
	v_fma_f32 v229, v68, v62, v229
	v_mov_b64_e32 v[62:63], v[228:229]
	s_nop 0
	v_cvt_pk_bf16_f32 v64, v62, v63
	ds_write_b16 v142, v64 offset:1632
	ds_write_b16_d16_hi v142, v64 offset:1760
	s_nop 0
	s_nop 0
	s_waitcnt lgkmcnt(15)
	v_fma_f32 v230, v66, v62, v230
	v_fma_f32 v231, v67, v63, v231
	v_fma_f32 v230, -v69, v63, v230
	v_fma_f32 v231, v68, v62, v231
	v_mov_b64_e32 v[62:63], v[230:231]
	s_nop 0
	v_cvt_pk_bf16_f32 v64, v62, v63
	ds_write_b16 v142, v64 offset:1904
	ds_write_b16_d16_hi v142, v64 offset:2032
	s_nop 0
	s_nop 0
	s_waitcnt lgkmcnt(15)
	v_fma_f32 v232, v66, v62, v232
	v_fma_f32 v233, v67, v63, v233
	v_fma_f32 v232, -v69, v63, v232
	v_fma_f32 v233, v68, v62, v233
	v_mov_b64_e32 v[62:63], v[232:233]
	s_nop 0
	v_cvt_pk_bf16_f32 v64, v62, v63
	ds_write_b16 v142, v64 offset:2176
	ds_write_b16_d16_hi v142, v64 offset:2304
	s_nop 0
	s_nop 0
	s_waitcnt lgkmcnt(15)
	v_fma_f32 v234, v66, v62, v234
	v_fma_f32 v235, v67, v63, v235
	v_fma_f32 v234, -v69, v63, v234
	v_fma_f32 v235, v68, v62, v235
	v_mov_b64_e32 v[62:63], v[234:235]
	s_nop 0
	v_cvt_pk_bf16_f32 v64, v62, v63
	ds_write_b16 v142, v64 offset:2448
	ds_write_b16_d16_hi v142, v64 offset:2576
	s_nop 0
	s_nop 0
	s_waitcnt lgkmcnt(15)
	v_fma_f32 v236, v66, v62, v236
	v_fma_f32 v237, v67, v63, v237
	v_fma_f32 v236, -v69, v63, v236
	v_fma_f32 v237, v68, v62, v237
	v_mov_b64_e32 v[62:63], v[236:237]
	s_nop 0
	v_cvt_pk_bf16_f32 v64, v62, v63
	ds_write_b16 v142, v64 offset:2720
	ds_write_b16_d16_hi v142, v64 offset:2848
	s_nop 0
	s_nop 0
	s_waitcnt lgkmcnt(15)
	v_fma_f32 v238, v66, v62, v238
	v_fma_f32 v239, v67, v63, v239
	v_fma_f32 v238, -v69, v63, v238
	v_fma_f32 v239, v68, v62, v239
	v_mov_b64_e32 v[62:63], v[238:239]
	s_nop 0
	v_cvt_pk_bf16_f32 v64, v62, v63
	ds_write_b16 v142, v64 offset:2992
	ds_write_b16_d16_hi v142, v64 offset:3120
	s_nop 0
	s_nop 0
	s_waitcnt lgkmcnt(15)
	v_fma_f32 v240, v66, v62, v240
	v_fma_f32 v241, v67, v63, v241
	v_fma_f32 v240, -v69, v63, v240
	v_fma_f32 v241, v68, v62, v241
	v_mov_b64_e32 v[62:63], v[240:241]
	s_nop 0
	v_cvt_pk_bf16_f32 v64, v62, v63
	ds_write_b16 v142, v64 offset:3264
	ds_write_b16_d16_hi v142, v64 offset:3392
	s_nop 0
	s_nop 0
	s_waitcnt lgkmcnt(15)
	v_fma_f32 v242, v66, v62, v242
	v_fma_f32 v243, v67, v63, v243
	v_fma_f32 v242, -v69, v63, v242
	v_fma_f32 v243, v68, v62, v243
	v_mov_b64_e32 v[62:63], v[242:243]
	s_nop 0
	v_cvt_pk_bf16_f32 v64, v62, v63
	ds_write_b16 v142, v64 offset:3536
	ds_write_b16_d16_hi v142, v64 offset:3664
	s_nop 0
	s_nop 0
	s_waitcnt lgkmcnt(15)
	v_fma_f32 v244, v66, v62, v244
	v_fma_f32 v245, v67, v63, v245
	v_fma_f32 v244, -v69, v63, v244
	v_fma_f32 v245, v68, v62, v245
	v_mov_b64_e32 v[62:63], v[244:245]
	s_nop 0
	v_cvt_pk_bf16_f32 v64, v62, v63
	ds_write_b16 v142, v64 offset:3808
	ds_write_b16_d16_hi v142, v64 offset:3936
	s_nop 0
	s_nop 0
	s_waitcnt lgkmcnt(15)
	v_fma_f32 v246, v66, v62, v246
	v_fma_f32 v247, v67, v63, v247
	v_fma_f32 v246, -v69, v63, v246
	v_fma_f32 v247, v68, v62, v247
	v_mov_b64_e32 v[128:129], v[246:247]
	s_nop 0
	v_cvt_pk_bf16_f32 v62, v128, v129
	ds_write_b16 v142, v62 offset:4080
	ds_write_b16_d16_hi v142, v62 offset:4208
	s_waitcnt lgkmcnt(0)
	ds_read_b128 v[62:65], v144
	ds_read_b128 v[186:189], v144 offset:64
	s_waitcnt lgkmcnt(1)
	v_mfma_f32_16x16x32_bf16 v[62:65], v[62:65], v[50:53], 0
	s_waitcnt lgkmcnt(0)
	v_mfma_f32_16x16x32_bf16 v[62:65], v[186:189], v[46:49], v[62:65]
	ds_read_b128 v[186:189], v144 offset:128
	s_waitcnt lgkmcnt(0)
	v_mfma_f32_16x16x32_bf16 v[62:65], v[186:189], v[42:45], v[62:65]
	ds_read_b128 v[186:189], v144 offset:192
	s_waitcnt lgkmcnt(0)
	v_mfma_f32_16x16x32_bf16 v[62:65], v[186:189], v[38:41], v[62:65]
	s_nop 7
	v_fma_f32 v62, v184, v149, v62
	v_mul_f32_e32 v132, 0x3d372713, v62
	v_mul_f32_e32 v132, v62, v132
	v_fma_f32 v132, v62, v132, v62
	v_mul_f32_e32 v132, 0xbfcc422a, v132
	v_mul_f32_e32 v132, 0x3fb8aa3b, v132
	v_exp_f32_e32 v132, v132
	v_fmac_f32_e32 v65, v181, v149
	v_add_f32_e32 v132, 1.0, v132
	v_rcp_f32_e32 v132, v132
	s_nop 0
	v_mul_f32_e32 v62, v62, v132
	v_cvt_pk_bf16_f32 v62, v62, v20
	ds_write_b16 v130, v62 offset:8448
	v_fma_f32 v62, v183, v149, v63
	v_mul_f32_e32 v63, 0x3d372713, v62
	v_mul_f32_e32 v63, v62, v63
	v_fma_f32 v63, v62, v63, v62
	v_mul_f32_e32 v63, 0xbfcc422a, v63
	v_mul_f32_e32 v63, 0x3fb8aa3b, v63
	v_exp_f32_e32 v63, v63
	s_nop 0
	v_add_f32_e32 v63, 1.0, v63
	v_rcp_f32_e32 v63, v63
	s_nop 0
	v_mul_f32_e32 v62, v62, v63
	v_cvt_pk_bf16_f32 v62, v62, v20
	ds_write_b16 v130, v62 offset:8976
	v_fma_f32 v62, v182, v149, v64
	v_mul_f32_e32 v63, 0x3d372713, v62
	v_mul_f32_e32 v63, v62, v63
	v_fma_f32 v63, v62, v63, v62
	v_mul_f32_e32 v63, 0xbfcc422a, v63
	v_mul_f32_e32 v63, 0x3fb8aa3b, v63
	v_exp_f32_e32 v63, v63
	s_nop 0
	v_add_f32_e32 v63, 1.0, v63
	v_rcp_f32_e32 v63, v63
	s_nop 0
	v_mul_f32_e32 v62, v62, v63
	v_cvt_pk_bf16_f32 v62, v62, v20
	ds_write_b16 v130, v62 offset:9504
	v_mul_f32_e32 v62, 0x3d372713, v65
	v_mul_f32_e32 v62, v65, v62
	v_fma_f32 v62, v65, v62, v65
	v_mul_f32_e32 v62, 0xbfcc422a, v62
	v_mul_f32_e32 v62, 0x3fb8aa3b, v62
	v_exp_f32_e32 v62, v62
	s_nop 0
	v_add_f32_e32 v62, 1.0, v62
	v_rcp_f32_e32 v62, v62
	s_nop 0
	v_mul_f32_e32 v62, v65, v62
	v_cvt_pk_bf16_f32 v62, v62, v20
	ds_write_b16 v130, v62 offset:10032
	s_waitcnt lgkmcnt(0)
	s_and_b64 vcc, exec, s[38:39]
	s_cbranch_vccz .LBB0_522

.LBB0_520:
	v_mfma_f32_16x16x32_bf16 v[30:33], v[54:57], v[30:33], 0
	v_mfma_f32_16x16x32_bf16 v[34:37], v[54:57], v[34:37], 0
	s_nop 7
	ds_write2_b32 v140, v30, v34 offset1:16
	ds_write2_b32 v140, v31, v35 offset0:132 offset1:148
	ds_write2_b32 v165, v32, v36 offset0:8 offset1:24
	v_mfma_f32_16x16x32_bf16 v[22:25], v[54:57], v[22:25], 0
	v_mfma_f32_16x16x32_bf16 v[26:29], v[54:57], v[26:29], 0
	ds_write2_b32 v165, v33, v37 offset0:140 offset1:156
	s_nop 6
	ds_write2_b32 v140, v22, v26 offset0:32 offset1:48
	ds_write2_b32 v140, v23, v27 offset0:164 offset1:180
	v_mfma_f32_16x16x32_bf16 v[16:19], v[54:57], v[16:19], 0
	v_mfma_f32_16x16x32_bf16 v[12:15], v[54:57], v[12:15], 0
	ds_write2_b32 v165, v24, v28 offset0:40 offset1:56
	ds_write2_b32 v165, v25, v29 offset0:172 offset1:188
	s_nop 5
	ds_write2_b32 v140, v16, v12 offset0:64 offset1:80
	ds_write2_b32 v140, v17, v13 offset0:196 offset1:212
	ds_write2_b32 v165, v18, v14 offset0:72 offset1:88
	ds_write2_b32 v165, v19, v15 offset0:204 offset1:220
	v_mfma_f32_16x16x32_bf16 v[8:11], v[54:57], v[8:11], 0
	v_mfma_f32_16x16x32_bf16 v[4:7], v[54:57], v[4:7], 0
	s_nop 7
	ds_write2_b32 v140, v8, v4 offset0:96 offset1:112
	ds_write2_b32 v140, v9, v5 offset0:228 offset1:244
	ds_write2_b32 v165, v10, v6 offset0:104 offset1:120
	ds_write2_b32 v165, v11, v7 offset0:236 offset1:252
	s_waitcnt lgkmcnt(0)
	ds_read2st64_b32 v[216:217], v141 offset1:1
	v_add_u32_e32 v207, 16, v141
	ds_read2st64_b32 v[218:219], v207 offset0:2 offset1:3
	v_add_u32_e32 v207, 32, v141
	ds_read2st64_b32 v[220:221], v207 offset0:4 offset1:5
	v_add_u32_e32 v207, 48, v141
	ds_read2st64_b32 v[222:223], v207 offset0:6 offset1:7
	v_add_u32_e32 v207, 64, v141
	ds_read2st64_b32 v[224:225], v207 offset0:8 offset1:9
	v_add_u32_e32 v207, 80, v141
	ds_read2st64_b32 v[226:227], v207 offset0:10 offset1:11
	v_add_u32_e32 v207, 96, v141
	ds_read2st64_b32 v[228:229], v207 offset0:12 offset1:13
	v_add_u32_e32 v207, 112, v141
	ds_read2st64_b32 v[230:231], v207 offset0:14 offset1:15
	v_add_u32_e32 v207, 128, v141
	ds_read2st64_b32 v[232:233], v207 offset0:16 offset1:17
	v_add_u32_e32 v207, 144, v141
	ds_read2st64_b32 v[234:235], v207 offset0:18 offset1:19
	v_add_u32_e32 v207, 160, v141
	ds_read2st64_b32 v[236:237], v207 offset0:20 offset1:21
	v_add_u32_e32 v207, 176, v141
	ds_read2st64_b32 v[238:239], v207 offset0:22 offset1:23
	v_add_u32_e32 v207, 192, v141
	ds_read2st64_b32 v[240:241], v207 offset0:24 offset1:25
	v_add_u32_e32 v207, 208, v141
	ds_read2st64_b32 v[242:243], v207 offset0:26 offset1:27
	v_add_u32_e32 v207, 224, v141
	ds_read2st64_b32 v[244:245], v207 offset0:28 offset1:29
	v_add_u32_e32 v207, 240, v141
	ds_read2st64_b32 v[246:247], v207 offset0:30 offset1:31
	s_nop 0
	s_nop 0
	s_waitcnt lgkmcnt(15)
	v_fma_f32 v216, v66, v128, v216
	v_fma_f32 v217, v67, v129, v217
	v_fma_f32 v216, -v69, v129, v216
	v_fma_f32 v217, v68, v128, v217
	v_mov_b64_e32 v[4:5], v[216:217]
	s_nop 0
	v_cvt_pk_bf16_f32 v6, v4, v5
	ds_write_b16 v142, v6
	ds_write_b16_d16_hi v142, v6 offset:128
	s_nop 0
	s_nop 0
	s_waitcnt lgkmcnt(15)
	v_fma_f32 v218, v66, v4, v218
	v_fma_f32 v219, v67, v5, v219
	v_fma_f32 v218, -v69, v5, v218
	v_fma_f32 v219, v68, v4, v219
	v_mov_b64_e32 v[4:5], v[218:219]
	s_nop 0
	v_cvt_pk_bf16_f32 v6, v4, v5
	ds_write_b16 v142, v6 offset:272
	ds_write_b16_d16_hi v142, v6 offset:400
	s_nop 0
	s_nop 0
	s_waitcnt lgkmcnt(15)
	v_fma_f32 v220, v66, v4, v220
	v_fma_f32 v221, v67, v5, v221
	v_fma_f32 v220, -v69, v5, v220
	v_fma_f32 v221, v68, v4, v221
	v_mov_b64_e32 v[4:5], v[220:221]
	s_nop 0
	v_cvt_pk_bf16_f32 v6, v4, v5
	ds_write_b16 v142, v6 offset:544
	ds_write_b16_d16_hi v142, v6 offset:672
	s_nop 0
	s_nop 0
	s_waitcnt lgkmcnt(15)
	v_fma_f32 v222, v66, v4, v222
	v_fma_f32 v223, v67, v5, v223
	v_fma_f32 v222, -v69, v5, v222
	v_fma_f32 v223, v68, v4, v223
	v_mov_b64_e32 v[4:5], v[222:223]
	s_nop 0
	v_cvt_pk_bf16_f32 v6, v4, v5
	ds_write_b16 v142, v6 offset:816
	ds_write_b16_d16_hi v142, v6 offset:944
	s_nop 0
	s_nop 0
	s_waitcnt lgkmcnt(15)
	v_fma_f32 v224, v66, v4, v224
	v_fma_f32 v225, v67, v5, v225
	v_fma_f32 v224, -v69, v5, v224
	v_fma_f32 v225, v68, v4, v225
	v_mov_b64_e32 v[4:5], v[224:225]
	s_nop 0
	v_cvt_pk_bf16_f32 v6, v4, v5
	ds_write_b16 v142, v6 offset:1088
	ds_write_b16_d16_hi v142, v6 offset:1216
	s_nop 0
	s_nop 0
	s_waitcnt lgkmcnt(15)
	v_fma_f32 v226, v66, v4, v226
	v_fma_f32 v227, v67, v5, v227
	v_fma_f32 v226, -v69, v5, v226
	v_fma_f32 v227, v68, v4, v227
	v_mov_b64_e32 v[4:5], v[226:227]
	s_nop 0
	v_cvt_pk_bf16_f32 v6, v4, v5
	ds_write_b16 v142, v6 offset:1360
	ds_write_b16_d16_hi v142, v6 offset:1488
	s_nop 0
	s_nop 0
	s_waitcnt lgkmcnt(15)
	v_fma_f32 v228, v66, v4, v228
	v_fma_f32 v229, v67, v5, v229
	v_fma_f32 v228, -v69, v5, v228
	v_fma_f32 v229, v68, v4, v229
	v_mov_b64_e32 v[4:5], v[228:229]
	s_nop 0
	v_cvt_pk_bf16_f32 v6, v4, v5
	ds_write_b16 v142, v6 offset:1632
	ds_write_b16_d16_hi v142, v6 offset:1760
	s_nop 0
	s_nop 0
	s_waitcnt lgkmcnt(15)
	v_fma_f32 v230, v66, v4, v230
	v_fma_f32 v231, v67, v5, v231
	v_fma_f32 v230, -v69, v5, v230
	v_fma_f32 v231, v68, v4, v231
	v_mov_b64_e32 v[4:5], v[230:231]
	s_nop 0
	v_cvt_pk_bf16_f32 v6, v4, v5
	ds_write_b16 v142, v6 offset:1904
	ds_write_b16_d16_hi v142, v6 offset:2032
	s_nop 0
	s_nop 0
	s_waitcnt lgkmcnt(15)
	v_fma_f32 v232, v66, v4, v232
	v_fma_f32 v233, v67, v5, v233
	v_fma_f32 v232, -v69, v5, v232
	v_fma_f32 v233, v68, v4, v233
	v_mov_b64_e32 v[4:5], v[232:233]
	s_nop 0
	v_cvt_pk_bf16_f32 v6, v4, v5
	ds_write_b16 v142, v6 offset:2176
	ds_write_b16_d16_hi v142, v6 offset:2304
	s_nop 0
	s_nop 0
	s_waitcnt lgkmcnt(15)
	v_fma_f32 v234, v66, v4, v234
	v_fma_f32 v235, v67, v5, v235
	v_fma_f32 v234, -v69, v5, v234
	v_fma_f32 v235, v68, v4, v235
	v_mov_b64_e32 v[4:5], v[234:235]
	s_nop 0
	v_cvt_pk_bf16_f32 v6, v4, v5
	ds_write_b16 v142, v6 offset:2448
	ds_write_b16_d16_hi v142, v6 offset:2576
	s_nop 0
	s_nop 0
	s_waitcnt lgkmcnt(15)
	v_fma_f32 v236, v66, v4, v236
	v_fma_f32 v237, v67, v5, v237
	v_fma_f32 v236, -v69, v5, v236
	v_fma_f32 v237, v68, v4, v237
	v_mov_b64_e32 v[4:5], v[236:237]
	s_nop 0
	v_cvt_pk_bf16_f32 v6, v4, v5
	ds_write_b16 v142, v6 offset:2720
	ds_write_b16_d16_hi v142, v6 offset:2848
	s_nop 0
	s_nop 0
	s_waitcnt lgkmcnt(15)
	v_fma_f32 v238, v66, v4, v238
	v_fma_f32 v239, v67, v5, v239
	v_fma_f32 v238, -v69, v5, v238
	v_fma_f32 v239, v68, v4, v239
	v_mov_b64_e32 v[4:5], v[238:239]
	s_nop 0
	v_cvt_pk_bf16_f32 v6, v4, v5
	ds_write_b16 v142, v6 offset:2992
	ds_write_b16_d16_hi v142, v6 offset:3120
	s_nop 0
	s_nop 0
	s_waitcnt lgkmcnt(15)
	v_fma_f32 v240, v66, v4, v240
	v_fma_f32 v241, v67, v5, v241
	v_fma_f32 v240, -v69, v5, v240
	v_fma_f32 v241, v68, v4, v241
	v_mov_b64_e32 v[4:5], v[240:241]
	s_nop 0
	v_cvt_pk_bf16_f32 v6, v4, v5
	ds_write_b16 v142, v6 offset:3264
	ds_write_b16_d16_hi v142, v6 offset:3392
	s_nop 0
	s_nop 0
	s_waitcnt lgkmcnt(15)
	v_fma_f32 v242, v66, v4, v242
	v_fma_f32 v243, v67, v5, v243
	v_fma_f32 v242, -v69, v5, v242
	v_fma_f32 v243, v68, v4, v243
	v_mov_b64_e32 v[4:5], v[242:243]
	s_nop 0
	v_cvt_pk_bf16_f32 v6, v4, v5
	ds_write_b16 v142, v6 offset:3536
	ds_write_b16_d16_hi v142, v6 offset:3664
	s_nop 0
	s_nop 0
	s_waitcnt lgkmcnt(15)
	v_fma_f32 v244, v66, v4, v244
	v_fma_f32 v245, v67, v5, v245
	v_fma_f32 v244, -v69, v5, v244
	v_fma_f32 v245, v68, v4, v245
	v_mov_b64_e32 v[4:5], v[244:245]
	s_nop 0
	v_cvt_pk_bf16_f32 v6, v4, v5
	ds_write_b16 v142, v6 offset:3808
	ds_write_b16_d16_hi v142, v6 offset:3936
	s_nop 0
	s_nop 0
	s_waitcnt lgkmcnt(15)
	v_fma_f32 v246, v66, v4, v246
	v_fma_f32 v247, v67, v5, v247
	v_fma_f32 v246, -v69, v5, v246
	v_fma_f32 v247, v68, v4, v247
	v_mov_b64_e32 v[128:129], v[246:247]
	s_nop 0
	v_cvt_pk_bf16_f32 v4, v128, v129
	ds_write_b16 v142, v4 offset:4080
	ds_write_b16_d16_hi v142, v4 offset:4208
	s_waitcnt lgkmcnt(0)
	ds_read_b128 v[4:7], v144
	ds_read_b128 v[8:11], v144 offset:64
	s_waitcnt lgkmcnt(1)
	v_mfma_f32_16x16x32_bf16 v[4:7], v[4:7], v[50:53], 0
	ds_read_b128 v[12:15], v144 offset:128
	s_waitcnt lgkmcnt(1)
	v_mfma_f32_16x16x32_bf16 v[4:7], v[8:11], v[46:49], v[4:7]
	ds_read_b128 v[8:11], v144 offset:192
	s_waitcnt lgkmcnt(1)
	v_mfma_f32_16x16x32_bf16 v[4:7], v[12:15], v[42:45], v[4:7]
	s_waitcnt lgkmcnt(0)
	v_mfma_f32_16x16x32_bf16 v[4:7], v[8:11], v[38:41], v[4:7]
	s_nop 7
	v_fma_f32 v4, v148, v149, v4
	v_mul_f32_e32 v8, 0x3d372713, v4
	v_mul_f32_e32 v8, v4, v8
	v_fma_f32 v5, v146, v149, v5
	v_fma_f32 v8, v4, v8, v4
	v_mul_f32_e32 v9, 0x3d372713, v5
	v_mul_f32_e32 v8, 0xbfcc422a, v8
	v_mul_f32_e32 v9, v5, v9
	v_mul_f32_e32 v8, 0x3fb8aa3b, v8
	v_fma_f32 v9, v5, v9, v5
	v_exp_f32_e32 v8, v8
	v_mul_f32_e32 v9, 0xbfcc422a, v9
	v_mul_f32_e32 v9, 0x3fb8aa3b, v9
	v_exp_f32_e32 v9, v9
	v_add_f32_e32 v8, 1.0, v8
	v_rcp_f32_e32 v8, v8
	v_fmac_f32_e32 v7, v131, v149
	v_add_f32_e32 v9, 1.0, v9
	v_rcp_f32_e32 v9, v9
	v_mul_f32_e32 v4, v4, v8
	v_cvt_pk_bf16_f32 v4, v4, v20
	ds_write_b16 v130, v4 offset:25344
	v_mul_f32_e32 v4, v5, v9
	v_fma_f32 v5, v147, v149, v6
	v_mul_f32_e32 v6, 0x3d372713, v5
	v_mul_f32_e32 v8, 0x3d372713, v7
	v_mul_f32_e32 v6, v5, v6
	v_mul_f32_e32 v8, v7, v8
	v_fma_f32 v6, v5, v6, v5
	v_fma_f32 v8, v7, v8, v7
	v_mul_f32_e32 v6, 0xbfcc422a, v6
	v_mul_f32_e32 v8, 0xbfcc422a, v8
	v_mul_f32_e32 v6, 0x3fb8aa3b, v6
	v_mul_f32_e32 v8, 0x3fb8aa3b, v8
	v_exp_f32_e32 v6, v6
	v_exp_f32_e32 v8, v8
	v_cvt_pk_bf16_f32 v4, v4, v20
	ds_write_b16 v130, v4 offset:25872
	v_add_f32_e32 v6, 1.0, v6
	v_add_f32_e32 v4, 1.0, v8
	v_rcp_f32_e32 v6, v6
	v_rcp_f32_e32 v4, v4
	v_mul_f32_e32 v5, v5, v6
	v_mul_f32_e32 v4, v7, v4
	v_cvt_pk_bf16_f32 v5, v5, v20
	ds_write_b16 v130, v5 offset:26400
	v_cvt_pk_bf16_f32 v4, v4, v20
	ds_write_b16 v130, v4 offset:26928
	s_waitcnt lgkmcnt(0)
	s_andn2_b64 vcc, exec, s[46:47]
	s_cbranch_vccnz .LBB0_484
	s_branch .LBB0_524

.LBB0_522:
	v_mfma_f32_16x16x32_bf16 v[62:65], v[58:61], v[30:33], 0
	v_mfma_f32_16x16x32_bf16 v[182:185], v[58:61], v[34:37], 0
	s_nop 7
	ds_write2_b32 v140, v62, v182 offset1:16
	ds_write2_b32 v140, v63, v183 offset0:132 offset1:148
	ds_write2_b32 v165, v64, v184 offset0:8 offset1:24
	ds_write2_b32 v165, v65, v185 offset0:140 offset1:156
	v_mfma_f32_16x16x32_bf16 v[62:65], v[58:61], v[22:25], 0
	v_mfma_f32_16x16x32_bf16 v[182:185], v[58:61], v[26:29], 0
	s_nop 7
	ds_write2_b32 v140, v62, v182 offset0:32 offset1:48
	ds_write2_b32 v140, v63, v183 offset0:164 offset1:180
	ds_write2_b32 v165, v64, v184 offset0:40 offset1:56
	ds_write2_b32 v165, v65, v185 offset0:172 offset1:188
	v_mfma_f32_16x16x32_bf16 v[62:65], v[58:61], v[16:19], 0
	v_mfma_f32_16x16x32_bf16 v[182:185], v[58:61], v[12:15], 0
	s_nop 7
	ds_write2_b32 v140, v62, v182 offset0:64 offset1:80
	ds_write2_b32 v140, v63, v183 offset0:196 offset1:212
	ds_write2_b32 v165, v64, v184 offset0:72 offset1:88
	ds_write2_b32 v165, v65, v185 offset0:204 offset1:220
	v_mfma_f32_16x16x32_bf16 v[62:65], v[58:61], v[8:11], 0
	v_mfma_f32_16x16x32_bf16 v[58:61], v[58:61], v[4:7], 0
	s_nop 7
	ds_write2_b32 v140, v62, v58 offset0:96 offset1:112
	ds_write2_b32 v140, v63, v59 offset0:228 offset1:244
	ds_write2_b32 v165, v64, v60 offset0:104 offset1:120
	ds_write2_b32 v165, v65, v61 offset0:236 offset1:252
	s_waitcnt lgkmcnt(0)
	ds_read2st64_b32 v[216:217], v141 offset1:1
	v_add_u32_e32 v207, 16, v141
	ds_read2st64_b32 v[218:219], v207 offset0:2 offset1:3
	v_add_u32_e32 v207, 32, v141
	ds_read2st64_b32 v[220:221], v207 offset0:4 offset1:5
	v_add_u32_e32 v207, 48, v141
	ds_read2st64_b32 v[222:223], v207 offset0:6 offset1:7
	v_add_u32_e32 v207, 64, v141
	ds_read2st64_b32 v[224:225], v207 offset0:8 offset1:9
	v_add_u32_e32 v207, 80, v141
	ds_read2st64_b32 v[226:227], v207 offset0:10 offset1:11
	v_add_u32_e32 v207, 96, v141
	ds_read2st64_b32 v[228:229], v207 offset0:12 offset1:13
	v_add_u32_e32 v207, 112, v141
	ds_read2st64_b32 v[230:231], v207 offset0:14 offset1:15
	v_add_u32_e32 v207, 128, v141
	ds_read2st64_b32 v[232:233], v207 offset0:16 offset1:17
	v_add_u32_e32 v207, 144, v141
	ds_read2st64_b32 v[234:235], v207 offset0:18 offset1:19
	v_add_u32_e32 v207, 160, v141
	ds_read2st64_b32 v[236:237], v207 offset0:20 offset1:21
	v_add_u32_e32 v207, 176, v141
	ds_read2st64_b32 v[238:239], v207 offset0:22 offset1:23
	v_add_u32_e32 v207, 192, v141
	ds_read2st64_b32 v[240:241], v207 offset0:24 offset1:25
	v_add_u32_e32 v207, 208, v141
	ds_read2st64_b32 v[242:243], v207 offset0:26 offset1:27
	v_add_u32_e32 v207, 224, v141
	ds_read2st64_b32 v[244:245], v207 offset0:28 offset1:29
	v_add_u32_e32 v207, 240, v141
	ds_read2st64_b32 v[246:247], v207 offset0:30 offset1:31
	s_nop 0
	s_nop 0
	s_waitcnt lgkmcnt(15)
	v_fma_f32 v216, v66, v128, v216
	v_fma_f32 v217, v67, v129, v217
	v_fma_f32 v216, -v69, v129, v216
	v_fma_f32 v217, v68, v128, v217
	v_mov_b64_e32 v[58:59], v[216:217]
	s_nop 0
	v_cvt_pk_bf16_f32 v60, v58, v59
	ds_write_b16 v142, v60
	ds_write_b16_d16_hi v142, v60 offset:128
	s_nop 0
	s_nop 0
	s_waitcnt lgkmcnt(15)
	v_fma_f32 v218, v66, v58, v218
	v_fma_f32 v219, v67, v59, v219
	v_fma_f32 v218, -v69, v59, v218
	v_fma_f32 v219, v68, v58, v219
	v_mov_b64_e32 v[58:59], v[218:219]
	s_nop 0
	v_cvt_pk_bf16_f32 v60, v58, v59
	ds_write_b16 v142, v60 offset:272
	ds_write_b16_d16_hi v142, v60 offset:400
	s_nop 0
	s_nop 0
	s_waitcnt lgkmcnt(15)
	v_fma_f32 v220, v66, v58, v220
	v_fma_f32 v221, v67, v59, v221
	v_fma_f32 v220, -v69, v59, v220
	v_fma_f32 v221, v68, v58, v221
	v_mov_b64_e32 v[58:59], v[220:221]
	s_nop 0
	v_cvt_pk_bf16_f32 v60, v58, v59
	ds_write_b16 v142, v60 offset:544
	ds_write_b16_d16_hi v142, v60 offset:672
	s_nop 0
	s_nop 0
	s_waitcnt lgkmcnt(15)
	v_fma_f32 v222, v66, v58, v222
	v_fma_f32 v223, v67, v59, v223
	v_fma_f32 v222, -v69, v59, v222
	v_fma_f32 v223, v68, v58, v223
	v_mov_b64_e32 v[58:59], v[222:223]
	s_nop 0
	v_cvt_pk_bf16_f32 v60, v58, v59
	ds_write_b16 v142, v60 offset:816
	ds_write_b16_d16_hi v142, v60 offset:944
	s_nop 0
	s_nop 0
	s_waitcnt lgkmcnt(15)
	v_fma_f32 v224, v66, v58, v224
	v_fma_f32 v225, v67, v59, v225
	v_fma_f32 v224, -v69, v59, v224
	v_fma_f32 v225, v68, v58, v225
	v_mov_b64_e32 v[58:59], v[224:225]
	s_nop 0
	v_cvt_pk_bf16_f32 v60, v58, v59
	ds_write_b16 v142, v60 offset:1088
	ds_write_b16_d16_hi v142, v60 offset:1216
	s_nop 0
	s_nop 0
	s_waitcnt lgkmcnt(15)
	v_fma_f32 v226, v66, v58, v226
	v_fma_f32 v227, v67, v59, v227
	v_fma_f32 v226, -v69, v59, v226
	v_fma_f32 v227, v68, v58, v227
	v_mov_b64_e32 v[58:59], v[226:227]
	s_nop 0
	v_cvt_pk_bf16_f32 v60, v58, v59
	ds_write_b16 v142, v60 offset:1360
	ds_write_b16_d16_hi v142, v60 offset:1488
	s_nop 0
	s_nop 0
	s_waitcnt lgkmcnt(15)
	v_fma_f32 v228, v66, v58, v228
	v_fma_f32 v229, v67, v59, v229
	v_fma_f32 v228, -v69, v59, v228
	v_fma_f32 v229, v68, v58, v229
	v_mov_b64_e32 v[58:59], v[228:229]
	s_nop 0
	v_cvt_pk_bf16_f32 v60, v58, v59
	ds_write_b16 v142, v60 offset:1632
	ds_write_b16_d16_hi v142, v60 offset:1760
	s_nop 0
	s_nop 0
	s_waitcnt lgkmcnt(15)
	v_fma_f32 v230, v66, v58, v230
	v_fma_f32 v231, v67, v59, v231
	v_fma_f32 v230, -v69, v59, v230
	v_fma_f32 v231, v68, v58, v231
	v_mov_b64_e32 v[58:59], v[230:231]
	s_nop 0
	v_cvt_pk_bf16_f32 v60, v58, v59
	ds_write_b16 v142, v60 offset:1904
	ds_write_b16_d16_hi v142, v60 offset:2032
	s_nop 0
	s_nop 0
	s_waitcnt lgkmcnt(15)
	v_fma_f32 v232, v66, v58, v232
	v_fma_f32 v233, v67, v59, v233
	v_fma_f32 v232, -v69, v59, v232
	v_fma_f32 v233, v68, v58, v233
	v_mov_b64_e32 v[58:59], v[232:233]
	s_nop 0
	v_cvt_pk_bf16_f32 v60, v58, v59
	ds_write_b16 v142, v60 offset:2176
	ds_write_b16_d16_hi v142, v60 offset:2304
	s_nop 0
	s_nop 0
	s_waitcnt lgkmcnt(15)
	v_fma_f32 v234, v66, v58, v234
	v_fma_f32 v235, v67, v59, v235
	v_fma_f32 v234, -v69, v59, v234
	v_fma_f32 v235, v68, v58, v235
	v_mov_b64_e32 v[58:59], v[234:235]
	s_nop 0
	v_cvt_pk_bf16_f32 v60, v58, v59
	ds_write_b16 v142, v60 offset:2448
	ds_write_b16_d16_hi v142, v60 offset:2576
	s_nop 0
	s_nop 0
	s_waitcnt lgkmcnt(15)
	v_fma_f32 v236, v66, v58, v236
	v_fma_f32 v237, v67, v59, v237
	v_fma_f32 v236, -v69, v59, v236
	v_fma_f32 v237, v68, v58, v237
	v_mov_b64_e32 v[58:59], v[236:237]
	s_nop 0
	v_cvt_pk_bf16_f32 v60, v58, v59
	ds_write_b16 v142, v60 offset:2720
	ds_write_b16_d16_hi v142, v60 offset:2848
	s_nop 0
	s_nop 0
	s_waitcnt lgkmcnt(15)
	v_fma_f32 v238, v66, v58, v238
	v_fma_f32 v239, v67, v59, v239
	v_fma_f32 v238, -v69, v59, v238
	v_fma_f32 v239, v68, v58, v239
	v_mov_b64_e32 v[58:59], v[238:239]
	s_nop 0
	v_cvt_pk_bf16_f32 v60, v58, v59
	ds_write_b16 v142, v60 offset:2992
	ds_write_b16_d16_hi v142, v60 offset:3120
	s_nop 0
	s_nop 0
	s_waitcnt lgkmcnt(15)
	v_fma_f32 v240, v66, v58, v240
	v_fma_f32 v241, v67, v59, v241
	v_fma_f32 v240, -v69, v59, v240
	v_fma_f32 v241, v68, v58, v241
	v_mov_b64_e32 v[58:59], v[240:241]
	s_nop 0
	v_cvt_pk_bf16_f32 v60, v58, v59
	ds_write_b16 v142, v60 offset:3264
	ds_write_b16_d16_hi v142, v60 offset:3392
	s_nop 0
	s_nop 0
	s_waitcnt lgkmcnt(15)
	v_fma_f32 v242, v66, v58, v242
	v_fma_f32 v243, v67, v59, v243
	v_fma_f32 v242, -v69, v59, v242
	v_fma_f32 v243, v68, v58, v243
	v_mov_b64_e32 v[58:59], v[242:243]
	s_nop 0
	v_cvt_pk_bf16_f32 v60, v58, v59
	ds_write_b16 v142, v60 offset:3536
	ds_write_b16_d16_hi v142, v60 offset:3664
	s_nop 0
	s_nop 0
	s_waitcnt lgkmcnt(15)
	v_fma_f32 v244, v66, v58, v244
	v_fma_f32 v245, v67, v59, v245
	v_fma_f32 v244, -v69, v59, v244
	v_fma_f32 v245, v68, v58, v245
	v_mov_b64_e32 v[58:59], v[244:245]
	s_nop 0
	v_cvt_pk_bf16_f32 v60, v58, v59
	ds_write_b16 v142, v60 offset:3808
	ds_write_b16_d16_hi v142, v60 offset:3936
	s_nop 0
	s_nop 0
	s_waitcnt lgkmcnt(15)
	v_fma_f32 v246, v66, v58, v246
	v_fma_f32 v247, v67, v59, v247
	v_fma_f32 v246, -v69, v59, v246
	v_fma_f32 v247, v68, v58, v247
	v_mov_b64_e32 v[128:129], v[246:247]
	s_nop 0
	v_cvt_pk_bf16_f32 v58, v128, v129
	ds_write_b16 v142, v58 offset:4080
	ds_write_b16_d16_hi v142, v58 offset:4208
	s_waitcnt lgkmcnt(0)
	ds_read_b128 v[58:61], v144
	ds_read_b128 v[62:65], v144 offset:64
	s_waitcnt lgkmcnt(1)
	v_mfma_f32_16x16x32_bf16 v[58:61], v[58:61], v[50:53], 0
	s_waitcnt lgkmcnt(0)
	v_mfma_f32_16x16x32_bf16 v[58:61], v[62:65], v[46:49], v[58:61]
	ds_read_b128 v[62:65], v144 offset:128
	s_waitcnt lgkmcnt(0)
	v_mfma_f32_16x16x32_bf16 v[58:61], v[62:65], v[42:45], v[58:61]
	ds_read_b128 v[62:65], v144 offset:192
	s_waitcnt lgkmcnt(0)
	v_mfma_f32_16x16x32_bf16 v[58:61], v[62:65], v[38:41], v[58:61]
	s_nop 7
	v_fma_f32 v58, v166, v149, v58
	v_mul_f32_e32 v62, 0x3d372713, v58
	v_mul_f32_e32 v62, v58, v62
	v_fma_f32 v62, v58, v62, v58
	v_mul_f32_e32 v62, 0xbfcc422a, v62
	v_mul_f32_e32 v62, 0x3fb8aa3b, v62
	v_exp_f32_e32 v62, v62
	v_fmac_f32_e32 v61, v162, v149
	v_add_f32_e32 v62, 1.0, v62
	v_rcp_f32_e32 v62, v62
	s_nop 0
	v_mul_f32_e32 v58, v58, v62
	v_cvt_pk_bf16_f32 v58, v58, v20
	ds_write_b16 v130, v58 offset:16896
	v_fma_f32 v58, v164, v149, v59
	v_mul_f32_e32 v59, 0x3d372713, v58
	v_mul_f32_e32 v59, v58, v59
	v_fma_f32 v59, v58, v59, v58
	v_mul_f32_e32 v59, 0xbfcc422a, v59
	v_mul_f32_e32 v59, 0x3fb8aa3b, v59
	v_exp_f32_e32 v59, v59
	s_nop 0
	v_add_f32_e32 v59, 1.0, v59
	v_rcp_f32_e32 v59, v59
	s_nop 0
	v_mul_f32_e32 v58, v58, v59
	v_cvt_pk_bf16_f32 v58, v58, v20
	ds_write_b16 v130, v58 offset:17424
	v_fma_f32 v58, v163, v149, v60
	v_mul_f32_e32 v59, 0x3d372713, v58
	v_mul_f32_e32 v59, v58, v59
	v_fma_f32 v59, v58, v59, v58
	v_mul_f32_e32 v59, 0xbfcc422a, v59
	v_mul_f32_e32 v59, 0x3fb8aa3b, v59
	v_exp_f32_e32 v59, v59
	s_nop 0
	v_add_f32_e32 v59, 1.0, v59
	v_rcp_f32_e32 v59, v59
	s_nop 0
	v_mul_f32_e32 v58, v58, v59
	v_cvt_pk_bf16_f32 v58, v58, v20
	ds_write_b16 v130, v58 offset:17952
	v_mul_f32_e32 v58, 0x3d372713, v61
	v_mul_f32_e32 v58, v61, v58
	v_fma_f32 v58, v61, v58, v61
	v_mul_f32_e32 v58, 0xbfcc422a, v58
	v_mul_f32_e32 v58, 0x3fb8aa3b, v58
	v_exp_f32_e32 v58, v58
	s_nop 0
	v_add_f32_e32 v58, 1.0, v58
	v_rcp_f32_e32 v58, v58
	s_nop 0
	v_mul_f32_e32 v58, v61, v58
	v_cvt_pk_bf16_f32 v58, v58, v20
	ds_write_b16 v130, v58 offset:18480
	s_waitcnt lgkmcnt(0)
	s_and_b64 vcc, exec, s[38:39]
	s_cbranch_vccz .LBB0_520

.LBB0_2090:
	s_and_b32 s4, s8, 0xffffffe0
	s_and_b32 s11, s10, 15
	v_add_u32_e32 v250, s4, v8
	v_ashrrev_i32_e32 v251, 31, v250
	v_lshlrev_b64 v[250:251], 11, v[250:251]
	v_lshl_add_u64 v[250:251], s[2:3], 0, v[250:251]
	s_lshl_b32 s24, s11, 7
	v_lshl_add_u64 v[250:251], v[250:251], 0, s[24:25]
	v_mov_b32_e32 v252, v4
	v_mov_b32_e32 v253, v20
	v_lshl_add_u64 v[250:251], v[250:251], 0, v[252:253]
	global_load_dwordx2 v[252:253], v[250:251], off
	v_or_b32_e32 v5, s4, v21
	v_mad_i64_i32 v[6:7], s[12:13], v5, s91, v[0:1]
	v_lshl_or_b32 v5, s11, 6, v21
	v_mul_u32_u24_e32 v5, 0xb00, v5
	v_lshlrev_b32_e32 v16, 1, v5
	v_mov_b32_e32 v17, v20
	v_add_co_u32_e32 v148, vcc, 0x16000, v6
	v_lshl_add_u64 v[146:147], v[2:3], 0, v[16:17]
	s_nop 0
	v_addc_co_u32_e32 v149, vcc, 0, v7, vcc
	v_add_co_u32_e32 v156, vcc, 0x16000, v146
	s_nop 1
	v_addc_co_u32_e32 v157, vcc, 0, v147, vcc
	v_add_co_u32_e32 v162, vcc, 0x2c000, v146
	s_nop 1
	v_addc_co_u32_e32 v163, vcc, 0, v147, vcc
	v_add_co_u32_e32 v164, vcc, 0x42000, v146
	s_nop 1
	v_addc_co_u32_e32 v165, vcc, 0, v147, vcc
	global_load_dwordx4 v[50:53], v[6:7], off
	global_load_dwordx4 v[54:57], v[148:149], off
	global_load_dwordx4 v[58:61], v[146:147], off
	global_load_dwordx4 v[62:65], v[156:157], off
	global_load_dwordx4 v[66:69], v[162:163], off
	global_load_dwordx4 v[70:73], v[164:165], off
	global_load_dwordx4 v[74:77], v[6:7], off offset:64
	global_load_dwordx4 v[78:81], v[148:149], off offset:64
	global_load_dwordx4 v[82:85], v[146:147], off offset:64
	global_load_dwordx4 v[86:89], v[156:157], off offset:64
	global_load_dwordx4 v[90:93], v[162:163], off offset:64
	global_load_dwordx4 v[94:97], v[164:165], off offset:64
	global_load_dwordx4 v[98:101], v[6:7], off offset:128
	global_load_dwordx4 v[102:105], v[148:149], off offset:128
	global_load_dwordx4 v[106:109], v[146:147], off offset:128
	global_load_dwordx4 v[110:113], v[156:157], off offset:128
	global_load_dwordx4 v[114:117], v[162:163], off offset:128
	global_load_dwordx4 v[118:121], v[164:165], off offset:128
	global_load_dwordx4 v[122:125], v[6:7], off offset:192
	global_load_dwordx4 v[126:129], v[148:149], off offset:192
	global_load_dwordx4 v[130:133], v[146:147], off offset:192
	global_load_dwordx4 v[134:137], v[156:157], off offset:192
	global_load_dwordx4 v[138:141], v[162:163], off offset:192
	global_load_dwordx4 v[142:145], v[164:165], off offset:192
	global_load_dwordx4 v[166:169], v[6:7], off offset:256
	global_load_dwordx4 v[170:173], v[148:149], off offset:256
	global_load_dwordx4 v[174:177], v[146:147], off offset:256
	global_load_dwordx4 v[178:181], v[156:157], off offset:256
	global_load_dwordx4 v[182:185], v[162:163], off offset:256
	global_load_dwordx4 v[186:189], v[164:165], off offset:256
	global_load_dwordx4 v[208:211], v[6:7], off offset:320
	global_load_dwordx4 v[212:215], v[148:149], off offset:320
	global_load_dwordx4 v[216:219], v[146:147], off offset:320
	global_load_dwordx4 v[220:223], v[156:157], off offset:320
	global_load_dwordx4 v[224:227], v[162:163], off offset:320
	global_load_dwordx4 v[228:231], v[164:165], off offset:320
	s_waitcnt vmcnt(30)
	v_mfma_f32_16x16x32_bf16 v[30:33], v[58:61], v[50:53], 0
	v_mfma_f32_16x16x32_bf16 v[42:45], v[62:65], v[50:53], 0
	v_mfma_f32_16x16x32_bf16 v[46:49], v[66:69], v[50:53], 0
	v_mfma_f32_16x16x32_bf16 v[16:19], v[70:73], v[50:53], 0
	v_mfma_f32_16x16x32_bf16 v[22:25], v[58:61], v[54:57], 0
	v_mfma_f32_16x16x32_bf16 v[34:37], v[62:65], v[54:57], 0
	v_mfma_f32_16x16x32_bf16 v[38:41], v[66:69], v[54:57], 0
	v_mfma_f32_16x16x32_bf16 v[26:29], v[70:73], v[54:57], 0
	global_load_dwordx4 v[50:53], v[6:7], off offset:384
	global_load_dwordx4 v[54:57], v[148:149], off offset:384
	global_load_dwordx4 v[58:61], v[146:147], off offset:384
	global_load_dwordx4 v[62:65], v[156:157], off offset:384
	global_load_dwordx4 v[66:69], v[162:163], off offset:384
	global_load_dwordx4 v[70:73], v[164:165], off offset:384
	s_waitcnt vmcnt(30)
	v_mfma_f32_16x16x32_bf16 v[30:33], v[82:85], v[74:77], v[30:33]
	v_mfma_f32_16x16x32_bf16 v[42:45], v[86:89], v[74:77], v[42:45]
	v_mfma_f32_16x16x32_bf16 v[46:49], v[90:93], v[74:77], v[46:49]
	v_mfma_f32_16x16x32_bf16 v[16:19], v[94:97], v[74:77], v[16:19]
	v_mfma_f32_16x16x32_bf16 v[22:25], v[82:85], v[78:81], v[22:25]
	v_mfma_f32_16x16x32_bf16 v[34:37], v[86:89], v[78:81], v[34:37]
	v_mfma_f32_16x16x32_bf16 v[38:41], v[90:93], v[78:81], v[38:41]
	v_mfma_f32_16x16x32_bf16 v[26:29], v[94:97], v[78:81], v[26:29]
	global_load_dwordx4 v[74:77], v[6:7], off offset:448
	global_load_dwordx4 v[78:81], v[148:149], off offset:448
	global_load_dwordx4 v[82:85], v[146:147], off offset:448
	global_load_dwordx4 v[86:89], v[156:157], off offset:448
	global_load_dwordx4 v[90:93], v[162:163], off offset:448
	global_load_dwordx4 v[94:97], v[164:165], off offset:448
	s_waitcnt vmcnt(30)
	v_mfma_f32_16x16x32_bf16 v[30:33], v[106:109], v[98:101], v[30:33]
	v_mfma_f32_16x16x32_bf16 v[42:45], v[110:113], v[98:101], v[42:45]
	v_mfma_f32_16x16x32_bf16 v[46:49], v[114:117], v[98:101], v[46:49]
	v_mfma_f32_16x16x32_bf16 v[16:19], v[118:121], v[98:101], v[16:19]
	v_mfma_f32_16x16x32_bf16 v[22:25], v[106:109], v[102:105], v[22:25]
	v_mfma_f32_16x16x32_bf16 v[34:37], v[110:113], v[102:105], v[34:37]
	v_mfma_f32_16x16x32_bf16 v[38:41], v[114:117], v[102:105], v[38:41]
	v_mfma_f32_16x16x32_bf16 v[26:29], v[118:121], v[102:105], v[26:29]
	global_load_dwordx4 v[98:101], v[6:7], off offset:512
	global_load_dwordx4 v[102:105], v[148:149], off offset:512
	global_load_dwordx4 v[106:109], v[146:147], off offset:512
	global_load_dwordx4 v[110:113], v[156:157], off offset:512
	global_load_dwordx4 v[114:117], v[162:163], off offset:512
	global_load_dwordx4 v[118:121], v[164:165], off offset:512
	s_waitcnt vmcnt(30)
	v_mfma_f32_16x16x32_bf16 v[30:33], v[130:133], v[122:125], v[30:33]
	v_mfma_f32_16x16x32_bf16 v[42:45], v[134:137], v[122:125], v[42:45]
	v_mfma_f32_16x16x32_bf16 v[46:49], v[138:141], v[122:125], v[46:49]
	v_mfma_f32_16x16x32_bf16 v[16:19], v[142:145], v[122:125], v[16:19]
	v_mfma_f32_16x16x32_bf16 v[22:25], v[130:133], v[126:129], v[22:25]
	v_mfma_f32_16x16x32_bf16 v[34:37], v[134:137], v[126:129], v[34:37]
	v_mfma_f32_16x16x32_bf16 v[38:41], v[138:141], v[126:129], v[38:41]
	v_mfma_f32_16x16x32_bf16 v[26:29], v[142:145], v[126:129], v[26:29]
	global_load_dwordx4 v[122:125], v[6:7], off offset:576
	global_load_dwordx4 v[126:129], v[148:149], off offset:576
	global_load_dwordx4 v[130:133], v[146:147], off offset:576
	global_load_dwordx4 v[134:137], v[156:157], off offset:576
	global_load_dwordx4 v[138:141], v[162:163], off offset:576
	global_load_dwordx4 v[142:145], v[164:165], off offset:576
	s_waitcnt vmcnt(30)
	v_mfma_f32_16x16x32_bf16 v[30:33], v[174:177], v[166:169], v[30:33]
	v_mfma_f32_16x16x32_bf16 v[42:45], v[178:181], v[166:169], v[42:45]
	v_mfma_f32_16x16x32_bf16 v[46:49], v[182:185], v[166:169], v[46:49]
	v_mfma_f32_16x16x32_bf16 v[16:19], v[186:189], v[166:169], v[16:19]
	v_mfma_f32_16x16x32_bf16 v[22:25], v[174:177], v[170:173], v[22:25]
	v_mfma_f32_16x16x32_bf16 v[34:37], v[178:181], v[170:173], v[34:37]
	v_mfma_f32_16x16x32_bf16 v[38:41], v[182:185], v[170:173], v[38:41]
	v_mfma_f32_16x16x32_bf16 v[26:29], v[186:189], v[170:173], v[26:29]
	global_load_dwordx4 v[166:169], v[6:7], off offset:640
	global_load_dwordx4 v[170:173], v[148:149], off offset:640
	global_load_dwordx4 v[174:177], v[146:147], off offset:640
	global_load_dwordx4 v[178:181], v[156:157], off offset:640
	global_load_dwordx4 v[182:185], v[162:163], off offset:640
	global_load_dwordx4 v[186:189], v[164:165], off offset:640
	s_waitcnt vmcnt(30)
	v_mfma_f32_16x16x32_bf16 v[30:33], v[216:219], v[208:211], v[30:33]
	v_mfma_f32_16x16x32_bf16 v[42:45], v[220:223], v[208:211], v[42:45]
	v_mfma_f32_16x16x32_bf16 v[46:49], v[224:227], v[208:211], v[46:49]
	v_mfma_f32_16x16x32_bf16 v[16:19], v[228:231], v[208:211], v[16:19]
	v_mfma_f32_16x16x32_bf16 v[22:25], v[216:219], v[212:215], v[22:25]
	v_mfma_f32_16x16x32_bf16 v[34:37], v[220:223], v[212:215], v[34:37]
	v_mfma_f32_16x16x32_bf16 v[38:41], v[224:227], v[212:215], v[38:41]
	v_mfma_f32_16x16x32_bf16 v[26:29], v[228:231], v[212:215], v[26:29]
	s_waitcnt vmcnt(24)
	v_mfma_f32_16x16x32_bf16 v[30:33], v[58:61], v[50:53], v[30:33]
	v_mfma_f32_16x16x32_bf16 v[42:45], v[62:65], v[50:53], v[42:45]
	v_mfma_f32_16x16x32_bf16 v[46:49], v[66:69], v[50:53], v[46:49]
	v_mfma_f32_16x16x32_bf16 v[16:19], v[70:73], v[50:53], v[16:19]
	v_mfma_f32_16x16x32_bf16 v[22:25], v[58:61], v[54:57], v[22:25]
	v_mfma_f32_16x16x32_bf16 v[34:37], v[62:65], v[54:57], v[34:37]
	v_mfma_f32_16x16x32_bf16 v[38:41], v[66:69], v[54:57], v[38:41]
	v_mfma_f32_16x16x32_bf16 v[26:29], v[70:73], v[54:57], v[26:29]
	s_waitcnt vmcnt(18)
	v_mfma_f32_16x16x32_bf16 v[30:33], v[82:85], v[74:77], v[30:33]
	v_mfma_f32_16x16x32_bf16 v[42:45], v[86:89], v[74:77], v[42:45]
	v_mfma_f32_16x16x32_bf16 v[46:49], v[90:93], v[74:77], v[46:49]
	v_mfma_f32_16x16x32_bf16 v[16:19], v[94:97], v[74:77], v[16:19]
	v_mfma_f32_16x16x32_bf16 v[22:25], v[82:85], v[78:81], v[22:25]
	v_mfma_f32_16x16x32_bf16 v[34:37], v[86:89], v[78:81], v[34:37]
	v_mfma_f32_16x16x32_bf16 v[38:41], v[90:93], v[78:81], v[38:41]
	v_mfma_f32_16x16x32_bf16 v[26:29], v[94:97], v[78:81], v[26:29]
	s_waitcnt vmcnt(12)
	v_mfma_f32_16x16x32_bf16 v[30:33], v[106:109], v[98:101], v[30:33]
	v_mfma_f32_16x16x32_bf16 v[42:45], v[110:113], v[98:101], v[42:45]
	v_mfma_f32_16x16x32_bf16 v[46:49], v[114:117], v[98:101], v[46:49]
	v_mfma_f32_16x16x32_bf16 v[16:19], v[118:121], v[98:101], v[16:19]
	v_mfma_f32_16x16x32_bf16 v[22:25], v[106:109], v[102:105], v[22:25]
	v_mfma_f32_16x16x32_bf16 v[34:37], v[110:113], v[102:105], v[34:37]
	v_mfma_f32_16x16x32_bf16 v[38:41], v[114:117], v[102:105], v[38:41]
	v_mfma_f32_16x16x32_bf16 v[26:29], v[118:121], v[102:105], v[26:29]
	s_waitcnt vmcnt(6)
	v_mfma_f32_16x16x32_bf16 v[30:33], v[130:133], v[122:125], v[30:33]
	v_mfma_f32_16x16x32_bf16 v[42:45], v[134:137], v[122:125], v[42:45]
	v_mfma_f32_16x16x32_bf16 v[46:49], v[138:141], v[122:125], v[46:49]
	v_mfma_f32_16x16x32_bf16 v[16:19], v[142:145], v[122:125], v[16:19]
	v_mfma_f32_16x16x32_bf16 v[22:25], v[130:133], v[126:129], v[22:25]
	v_mfma_f32_16x16x32_bf16 v[34:37], v[134:137], v[126:129], v[34:37]
	v_mfma_f32_16x16x32_bf16 v[38:41], v[138:141], v[126:129], v[38:41]
	v_mfma_f32_16x16x32_bf16 v[26:29], v[142:145], v[126:129], v[26:29]
	s_waitcnt vmcnt(0)
	v_mfma_f32_16x16x32_bf16 v[30:33], v[174:177], v[166:169], v[30:33]
	v_mfma_f32_16x16x32_bf16 v[42:45], v[178:181], v[166:169], v[42:45]
	v_mfma_f32_16x16x32_bf16 v[46:49], v[182:185], v[166:169], v[46:49]
	v_mfma_f32_16x16x32_bf16 v[16:19], v[186:189], v[166:169], v[16:19]
	v_mfma_f32_16x16x32_bf16 v[22:25], v[174:177], v[170:173], v[22:25]
	v_mfma_f32_16x16x32_bf16 v[34:37], v[178:181], v[170:173], v[34:37]
	v_mfma_f32_16x16x32_bf16 v[38:41], v[182:185], v[170:173], v[38:41]
	v_mfma_f32_16x16x32_bf16 v[26:29], v[186:189], v[170:173], v[26:29]
	s_nop 7
	ds_write_b128 v14, v[30:33]
	ds_write_b128 v14, v[42:45] offset:64
	ds_write_b128 v14, v[46:49] offset:128
	s_nop 0
	ds_write_b128 v14, v[16:19] offset:192
	ds_write_b128 v14, v[22:25] offset:4096
	ds_write_b128 v14, v[34:37] offset:4160
	ds_write_b128 v14, v[38:41] offset:4224
	ds_write_b128 v14, v[26:29] offset:4288
	s_waitcnt lgkmcnt(0)
	s_barrier
	ds_read_b128 v[16:19], v9
	ds_read_b128 v[22:25], v9 offset:8192
	s_lshl_b32 s24, s11, 7
	v_mov_b32_e32 v5, v20
	s_waitcnt lgkmcnt(0)
	v_pk_add_f32 v[6:7], v[18:19], v[24:25]
	v_pk_add_f32 v[22:23], v[16:17], v[22:23]
	ds_read_b128 v[16:19], v9 offset:16384
	s_waitcnt lgkmcnt(0)
	v_pk_add_f32 v[6:7], v[6:7], v[18:19]
	v_pk_add_f32 v[22:23], v[22:23], v[16:17]
	ds_read_b128 v[16:19], v9 offset:24576
	s_waitcnt lgkmcnt(0)
	v_pk_add_f32 v[6:7], v[6:7], v[18:19]
	v_pk_add_f32 v[22:23], v[22:23], v[16:17]
	ds_read_b128 v[16:19], v9 offset:32768
	s_waitcnt lgkmcnt(0)
	v_pk_add_f32 v[6:7], v[6:7], v[18:19]
	v_pk_add_f32 v[22:23], v[22:23], v[16:17]
	ds_read_b128 v[16:19], v9 offset:40960
	s_waitcnt lgkmcnt(0)
	v_pk_add_f32 v[6:7], v[6:7], v[18:19]
	v_pk_add_f32 v[22:23], v[22:23], v[16:17]
	ds_read_b128 v[16:19], v9 offset:49152
	s_waitcnt lgkmcnt(0)
	v_pk_add_f32 v[6:7], v[6:7], v[18:19]
	v_pk_add_f32 v[22:23], v[22:23], v[16:17]
	ds_read_b128 v[16:19], v9 offset:57344
	s_waitcnt lgkmcnt(0)
	v_pk_add_f32 v[18:19], v[6:7], v[18:19]
	v_add_u32_e32 v6, s4, v8
	v_ashrrev_i32_e32 v7, 31, v6
	v_pk_add_f32 v[16:17], v[22:23], v[16:17]
	v_lshlrev_b64 v[22:23], 11, v[6:7]
	v_lshl_add_u64 v[22:23], s[2:3], 0, v[22:23]
	v_lshl_add_u64 v[22:23], v[22:23], 0, s[24:25]
	v_lshl_add_u64 v[22:23], v[22:23], 0, v[4:5]
	v_mov_b64_e32 v[24:25], v[252:253]
	s_waitcnt vmcnt(0)
	v_lshlrev_b32_e32 v26, 16, v24
	v_and_b32_e32 v27, 0xffff0000, v24
	v_lshlrev_b32_e32 v24, 16, v25
	v_and_b32_e32 v25, 0xffff0000, v25
	v_pk_fma_f32 v[18:19], v[18:19], 0.5, v[24:25] op_sel_hi:[1,0,1]
	v_pk_fma_f32 v[16:17], v[16:17], 0.5, v[26:27] op_sel_hi:[1,0,1]
	v_mul_f32_e32 v15, v19, v19
	v_mul_f32_e32 v5, v17, v17
	v_fmac_f32_e32 v5, v16, v16
	v_fmac_f32_e32 v15, v18, v18
	v_add_f32_e32 v5, v5, v15
	ds_bpermute_b32 v15, v10, v5
	v_cvt_pk_bf16_f32 v24, v16, v17
	v_cvt_pk_bf16_f32 v25, v18, v19
	global_store_dwordx2 v[22:23], v[24:25], off
	s_waitcnt lgkmcnt(0)
	v_add_f32_e32 v5, v5, v15
	ds_bpermute_b32 v15, v11, v5
	s_waitcnt lgkmcnt(0)
	v_add_f32_e32 v5, v5, v15
	ds_bpermute_b32 v15, v12, v5
	s_waitcnt lgkmcnt(0)
	v_add_f32_e32 v5, v5, v15
	ds_bpermute_b32 v15, v13, v5
	s_and_saveexec_b64 s[4:5], s[38:39]
	s_cbranch_execz .LBB0_2089
	v_lshlrev_b64 v[6:7], 6, v[6:7]
	v_lshl_add_u64 v[6:7], s[6:7], 0, v[6:7]
	s_lshl_b32 s24, s11, 2
	s_waitcnt lgkmcnt(0)
	v_add_f32_e32 v5, v5, v15
	v_lshl_add_u64 v[6:7], v[6:7], 0, s[24:25]
	global_store_dword v[6:7], v5, off
	s_branch .LBB0_2089
